# write-through (sc1) stores for PROJ (G1 epilogues) and CAT (attention tail) so the pair-barrier L2 writeback has less to flush
# speedup vs baseline: 1.0127x; 1.0127x over previous
; __device__ __forceinline__ unsigned cvt_pk_bf16(float lo, float hi) { unsigned r; asm volatile("v_cvt_pk_bf16_f32 %0, %1, %2" : "=v"(r) : "v"(lo), "v"(hi)); return r; }
;     __device__ __forceinline__ void operator()(const f32x4 (&acc)[2][2][4][2], const Unit& u, int wr, int wc, int fr, int fq) const {
;         const int row0 = u.pm * BM + wr * 64 + fr;
;         if (u.pn < 8) {
;             const float sc = (u.pn < 4) ? QSCALE : 1.f;
;             const int col = u.pn * BM + 64 * wc + 8 * fq;
; #pragma unroll
;             for (int ai = 0; ai < 2; ++ai)
; #pragma unroll
;                 for (int m = 0; m < 4; ++m) { const int row = row0 + ai * HALF + m * 16; const int pos = row & 4095;
;                     const float rs = sc * rstd[row & 255];
;                     const f32x4 c0 = *(const f32x4*)(cosT + pos * 32 + 8 * fq), c1 = *(const f32x4*)(cosT + pos * 32 + 8 * fq + 4);
;                     const f32x4 s0 = *(const f32x4*)(sinT + pos * 32 + 8 * fq), s1 = *(const f32x4*)(sinT + pos * 32 + 8 * fq + 4);
;                     const f32x4 a0 = acc[ai][0][m][0], a1 = acc[ai][0][m][1], b0 = acc[ai][1][m][0], b1 = acc[ai][1][m][1];
;                     const f32x4 x0 = (a0 * c0 - b0 * s0) * rs, x1 = (a1 * c1 - b1 * s1) * rs, y0 = (b0 * c0 + a0 * s0) * rs, y1 = (b1 * c1 + a1 * s1) * rs;
;                     bf16_t* rowp = O + (size_t)row * ldc + col;
;                     u32x4 w; w.x = cvt_pk_bf16(x0[0], x0[1]); w.y = cvt_pk_bf16(x0[2], x0[3]); w.z = cvt_pk_bf16(x1[0], x1[1]); w.w = cvt_pk_bf16(x1[2], x1[3]);
;                     *(u32x4*)rowp = w;
;                     w.x = cvt_pk_bf16(y0[0], y0[1]); w.y = cvt_pk_bf16(y0[2], y0[3]); w.z = cvt_pk_bf16(y1[0], y1[1]); w.w = cvt_pk_bf16(y1[2], y1[3]);
;                     *(u32x4*)(rowp + 32) = w; }
.LBB0_142:
	v_lshlrev_b32_e32 v197, 7, v155
	v_and_b32_e32 v197, 0x7ff80, v197
	ds_read_b32 v250, v152
	v_mov_b32_e32 v162, v197
	v_lshl_add_u64 v[198:199], v[138:139], 0, v[162:163]
	global_load_dwordx4 v[174:177], v[198:199], off
	global_load_dwordx4 v[178:181], v[198:199], off offset:16
	v_lshl_add_u64 v[198:199], v[136:137], 0, v[162:163]
	global_load_dwordx4 v[182:185], v[198:199], off
	global_load_dwordx4 v[186:189], v[198:199], off offset:16
	v_or_b32_e32 v162, 0x800, v197
	v_lshl_add_u64 v[198:199], v[138:139], 0, v[162:163]
	global_load_dwordx4 v[206:209], v[198:199], off
	global_load_dwordx4 v[210:213], v[198:199], off offset:16
	v_lshl_add_u64 v[198:199], v[136:137], 0, v[162:163]
	global_load_dwordx4 v[214:217], v[198:199], off
	global_load_dwordx4 v[218:221], v[198:199], off offset:16
	v_or_b32_e32 v162, 0x1000, v197
	v_lshl_add_u64 v[198:199], v[138:139], 0, v[162:163]
	global_load_dwordx4 v[222:225], v[198:199], off
	global_load_dwordx4 v[226:229], v[198:199], off offset:16
	v_lshl_add_u64 v[198:199], v[136:137], 0, v[162:163]
	global_load_dwordx4 v[230:233], v[198:199], off
	global_load_dwordx4 v[234:237], v[198:199], off offset:16
	v_or_b32_e32 v162, 0x1800, v197
	v_lshl_add_u64 v[198:199], v[138:139], 0, v[162:163]
	global_load_dwordx4 v[238:241], v[198:199], off
	global_load_dwordx4 v[242:245], v[198:199], off offset:16
	v_lshl_add_u64 v[198:199], v[136:137], 0, v[162:163]
	global_load_dwordx4 v[144:147], v[198:199], off
	global_load_dwordx4 v[156:159], v[198:199], off offset:16
	v_mul_u32_u24_e32 v196, 0x3000, v155
	v_lshl_or_b32 v162, s76, 8, v153
	v_lshl_add_u32 v196, v162, 1, v196
	s_cmp_lt_i32 s76, 4
	s_cselect_b32 s21, 0x3e38aa3b, 1.0
	s_waitcnt lgkmcnt(0)
	v_mul_f32_e32 v250, s21, v250
	ds_read_b32 v251, v152 offset:64
	s_waitcnt vmcnt(12)
	v_pk_mul_f32 v[246:247], v[116:117], v[174:175]
	v_pk_mul_f32 v[174:175], v[124:125], v[174:175]
	v_pk_fma_f32 v[124:125], v[124:125], v[182:183], v[246:247] neg_lo:[0,0,1] neg_hi:[0,0,1]
	v_pk_fma_f32 v[116:117], v[116:117], v[182:183], v[174:175]
	v_pk_mul_f32 v[248:249], v[118:119], v[176:177]
	v_pk_mul_f32 v[176:177], v[126:127], v[176:177]
	v_pk_fma_f32 v[126:127], v[126:127], v[184:185], v[248:249] neg_lo:[0,0,1] neg_hi:[0,0,1]
	v_pk_fma_f32 v[118:119], v[118:119], v[184:185], v[176:177]
	v_pk_mul_f32 v[246:247], v[112:113], v[178:179]
	v_pk_mul_f32 v[178:179], v[120:121], v[178:179]
	v_pk_fma_f32 v[120:121], v[120:121], v[186:187], v[246:247] neg_lo:[0,0,1] neg_hi:[0,0,1]
	v_pk_fma_f32 v[112:113], v[112:113], v[186:187], v[178:179]
	v_pk_mul_f32 v[248:249], v[114:115], v[180:181]
	v_pk_mul_f32 v[180:181], v[122:123], v[180:181]
	v_pk_fma_f32 v[122:123], v[122:123], v[188:189], v[248:249] neg_lo:[0,0,1] neg_hi:[0,0,1]
	v_pk_fma_f32 v[114:115], v[114:115], v[188:189], v[180:181]
	v_pk_mul_f32 v[124:125], v[250:251], v[124:125] op_sel_hi:[0,1]
	v_pk_mul_f32 v[126:127], v[250:251], v[126:127] op_sel_hi:[0,1]
	v_pk_mul_f32 v[120:121], v[250:251], v[120:121] op_sel_hi:[0,1]
	v_pk_mul_f32 v[122:123], v[250:251], v[122:123] op_sel_hi:[0,1]
	v_pk_mul_f32 v[116:117], v[250:251], v[116:117] op_sel_hi:[0,1]
	v_pk_mul_f32 v[118:119], v[250:251], v[118:119] op_sel_hi:[0,1]
	v_pk_mul_f32 v[112:113], v[250:251], v[112:113] op_sel_hi:[0,1]
	v_pk_mul_f32 v[114:115], v[250:251], v[114:115] op_sel_hi:[0,1]
	v_cvt_pk_bf16_f32 v182, v124, v125
	v_cvt_pk_bf16_f32 v183, v126, v127
	v_cvt_pk_bf16_f32 v184, v120, v121
	v_cvt_pk_bf16_f32 v185, v122, v123
	v_cvt_pk_bf16_f32 v186, v116, v117
	v_cvt_pk_bf16_f32 v187, v118, v119
	v_cvt_pk_bf16_f32 v188, v112, v113
	v_cvt_pk_bf16_f32 v189, v114, v115
	v_mov_b32_e32 v246, v196
	global_store_dwordx4 v246, v[182:185], s[66:67] sc1
	global_store_dwordx4 v246, v[186:189], s[66:67] offset:64 sc1
	v_or_b32_e32 v162, 0x4000, v197
	v_lshl_add_u64 v[198:199], v[138:139], 0, v[162:163]
	global_load_dwordx4 v[124:127], v[198:199], off
	global_load_dwordx4 v[120:123], v[198:199], off offset:16
	v_lshl_add_u64 v[198:199], v[136:137], 0, v[162:163]
	global_load_dwordx4 v[116:119], v[198:199], off
	global_load_dwordx4 v[112:115], v[198:199], off offset:16
	s_waitcnt lgkmcnt(0)
	v_mul_f32_e32 v251, s21, v251
	ds_read_b32 v250, v152 offset:128
	s_waitcnt vmcnt(14)
	v_pk_mul_f32 v[246:247], v[100:101], v[206:207]
	v_pk_mul_f32 v[206:207], v[108:109], v[206:207]
	v_pk_fma_f32 v[108:109], v[108:109], v[214:215], v[246:247] neg_lo:[0,0,1] neg_hi:[0,0,1]
	v_pk_fma_f32 v[100:101], v[100:101], v[214:215], v[206:207]
	v_pk_mul_f32 v[248:249], v[102:103], v[208:209]
	v_pk_mul_f32 v[208:209], v[110:111], v[208:209]
	v_pk_fma_f32 v[110:111], v[110:111], v[216:217], v[248:249] neg_lo:[0,0,1] neg_hi:[0,0,1]
	v_pk_fma_f32 v[102:103], v[102:103], v[216:217], v[208:209]
	v_pk_mul_f32 v[246:247], v[96:97], v[210:211]
	v_pk_mul_f32 v[210:211], v[104:105], v[210:211]
	v_pk_fma_f32 v[104:105], v[104:105], v[218:219], v[246:247] neg_lo:[0,0,1] neg_hi:[0,0,1]
	v_pk_fma_f32 v[96:97], v[96:97], v[218:219], v[210:211]
	v_pk_mul_f32 v[248:249], v[98:99], v[212:213]
	v_pk_mul_f32 v[212:213], v[106:107], v[212:213]
	v_pk_fma_f32 v[106:107], v[106:107], v[220:221], v[248:249] neg_lo:[0,0,1] neg_hi:[0,0,1]
	v_pk_fma_f32 v[98:99], v[98:99], v[220:221], v[212:213]
	v_pk_mul_f32 v[108:109], v[250:251], v[108:109] op_sel:[1,0] op_sel_hi:[1,1]
	v_pk_mul_f32 v[110:111], v[250:251], v[110:111] op_sel:[1,0] op_sel_hi:[1,1]
	v_pk_mul_f32 v[104:105], v[250:251], v[104:105] op_sel:[1,0] op_sel_hi:[1,1]
	v_pk_mul_f32 v[106:107], v[250:251], v[106:107] op_sel:[1,0] op_sel_hi:[1,1]
	v_pk_mul_f32 v[100:101], v[250:251], v[100:101] op_sel:[1,0] op_sel_hi:[1,1]
	v_pk_mul_f32 v[102:103], v[250:251], v[102:103] op_sel:[1,0] op_sel_hi:[1,1]
	v_pk_mul_f32 v[96:97], v[250:251], v[96:97] op_sel:[1,0] op_sel_hi:[1,1]
	v_pk_mul_f32 v[98:99], v[250:251], v[98:99] op_sel:[1,0] op_sel_hi:[1,1]
	v_cvt_pk_bf16_f32 v214, v108, v109
	v_cvt_pk_bf16_f32 v215, v110, v111
	v_cvt_pk_bf16_f32 v216, v104, v105
	v_cvt_pk_bf16_f32 v217, v106, v107
	v_cvt_pk_bf16_f32 v218, v100, v101
	v_cvt_pk_bf16_f32 v219, v102, v103
	v_cvt_pk_bf16_f32 v220, v96, v97
	v_cvt_pk_bf16_f32 v221, v98, v99
	v_add_u32_e32 v246, 0x30000, v196
	global_store_dwordx4 v246, v[214:217], s[66:67] sc1
	global_store_dwordx4 v246, v[218:221], s[66:67] offset:64 sc1
	v_or_b32_e32 v162, 0x4800, v197
	v_lshl_add_u64 v[198:199], v[138:139], 0, v[162:163]
	global_load_dwordx4 v[108:111], v[198:199], off
	global_load_dwordx4 v[104:107], v[198:199], off offset:16
	v_lshl_add_u64 v[198:199], v[136:137], 0, v[162:163]
	global_load_dwordx4 v[100:103], v[198:199], off
	global_load_dwordx4 v[96:99], v[198:199], off offset:16
	s_waitcnt lgkmcnt(0)
; __device__ __forceinline__ unsigned cvt_pk_bf16(float lo, float hi) { unsigned r; asm volatile("v_cvt_pk_bf16_f32 %0, %1, %2" : "=v"(r) : "v"(lo), "v"(hi)); return r; }
;     __device__ __forceinline__ void operator()(const f32x4 (&acc)[2][2][4][2], const Unit& u, int wr, int wc, int fr, int fq) const {
;     ...
;                 for (int m = 0; m < 4; ++m) { const int row = row0 + ai * HALF + m * 16; const int pos = row & 4095;
;                     const float rs = sc * rstd[row & 255];
;                     const f32x4 c0 = *(const f32x4*)(cosT + pos * 32 + 8 * fq), c1 = *(const f32x4*)(cosT + pos * 32 + 8 * fq + 4);
;                     const f32x4 s0 = *(const f32x4*)(sinT + pos * 32 + 8 * fq), s1 = *(const f32x4*)(sinT + pos * 32 + 8 * fq + 4);
;                     const f32x4 a0 = acc[ai][0][m][0], a1 = acc[ai][0][m][1], b0 = acc[ai][1][m][0], b1 = acc[ai][1][m][1];
;                     const f32x4 x0 = (a0 * c0 - b0 * s0) * rs, x1 = (a1 * c1 - b1 * s1) * rs, y0 = (b0 * c0 + a0 * s0) * rs, y1 = (b1 * c1 + a1 * s1) * rs;
;                     bf16_t* rowp = O + (size_t)row * ldc + col;
;                     u32x4 w; w.x = cvt_pk_bf16(x0[0], x0[1]); w.y = cvt_pk_bf16(x0[2], x0[3]); w.z = cvt_pk_bf16(x1[0], x1[1]); w.w = cvt_pk_bf16(x1[2], x1[3]);
;                     *(u32x4*)rowp = w;
;                     w.x = cvt_pk_bf16(y0[0], y0[1]); w.y = cvt_pk_bf16(y0[2], y0[3]); w.z = cvt_pk_bf16(y1[0], y1[1]); w.w = cvt_pk_bf16(y1[2], y1[3]);
;                     *(u32x4*)(rowp + 32) = w; }
	v_mul_f32_e32 v250, s21, v250
	ds_read_b32 v251, v152 offset:192
	s_waitcnt vmcnt(16)
	v_pk_mul_f32 v[246:247], v[84:85], v[222:223]
	v_pk_mul_f32 v[222:223], v[92:93], v[222:223]
	v_pk_fma_f32 v[92:93], v[92:93], v[230:231], v[246:247] neg_lo:[0,0,1] neg_hi:[0,0,1]
	v_pk_fma_f32 v[84:85], v[84:85], v[230:231], v[222:223]
	v_pk_mul_f32 v[248:249], v[86:87], v[224:225]
	v_pk_mul_f32 v[224:225], v[94:95], v[224:225]
	v_pk_fma_f32 v[94:95], v[94:95], v[232:233], v[248:249] neg_lo:[0,0,1] neg_hi:[0,0,1]
	v_pk_fma_f32 v[86:87], v[86:87], v[232:233], v[224:225]
	v_pk_mul_f32 v[246:247], v[80:81], v[226:227]
	v_pk_mul_f32 v[226:227], v[88:89], v[226:227]
	v_pk_fma_f32 v[88:89], v[88:89], v[234:235], v[246:247] neg_lo:[0,0,1] neg_hi:[0,0,1]
	v_pk_fma_f32 v[80:81], v[80:81], v[234:235], v[226:227]
	v_pk_mul_f32 v[248:249], v[82:83], v[228:229]
	v_pk_mul_f32 v[228:229], v[90:91], v[228:229]
	v_pk_fma_f32 v[90:91], v[90:91], v[236:237], v[248:249] neg_lo:[0,0,1] neg_hi:[0,0,1]
	v_pk_fma_f32 v[82:83], v[82:83], v[236:237], v[228:229]
	v_pk_mul_f32 v[92:93], v[250:251], v[92:93] op_sel_hi:[0,1]
	v_pk_mul_f32 v[94:95], v[250:251], v[94:95] op_sel_hi:[0,1]
	v_pk_mul_f32 v[88:89], v[250:251], v[88:89] op_sel_hi:[0,1]
	v_pk_mul_f32 v[90:91], v[250:251], v[90:91] op_sel_hi:[0,1]
	v_pk_mul_f32 v[84:85], v[250:251], v[84:85] op_sel_hi:[0,1]
	v_pk_mul_f32 v[86:87], v[250:251], v[86:87] op_sel_hi:[0,1]
	v_pk_mul_f32 v[80:81], v[250:251], v[80:81] op_sel_hi:[0,1]
	v_pk_mul_f32 v[82:83], v[250:251], v[82:83] op_sel_hi:[0,1]
	v_cvt_pk_bf16_f32 v230, v92, v93
	v_cvt_pk_bf16_f32 v231, v94, v95
	v_cvt_pk_bf16_f32 v232, v88, v89
	v_cvt_pk_bf16_f32 v233, v90, v91
	v_cvt_pk_bf16_f32 v234, v84, v85
	v_cvt_pk_bf16_f32 v235, v86, v87
	v_cvt_pk_bf16_f32 v236, v80, v81
	v_cvt_pk_bf16_f32 v237, v82, v83
	v_add_u32_e32 v246, 0x60000, v196
	global_store_dwordx4 v246, v[230:233], s[66:67] sc1
	global_store_dwordx4 v246, v[234:237], s[66:67] offset:64 sc1
	v_or_b32_e32 v162, 0x5000, v197
	v_lshl_add_u64 v[198:199], v[138:139], 0, v[162:163]
	global_load_dwordx4 v[92:95], v[198:199], off
	global_load_dwordx4 v[88:91], v[198:199], off offset:16
	v_lshl_add_u64 v[198:199], v[136:137], 0, v[162:163]
	global_load_dwordx4 v[84:87], v[198:199], off
	global_load_dwordx4 v[80:83], v[198:199], off offset:16
	s_waitcnt lgkmcnt(0)
	v_mul_f32_e32 v251, s21, v251
	ds_read_b32 v250, v152 offset:512
	s_waitcnt vmcnt(18)
	v_pk_mul_f32 v[246:247], v[68:69], v[238:239]
	v_pk_mul_f32 v[238:239], v[76:77], v[238:239]
	v_pk_fma_f32 v[76:77], v[76:77], v[144:145], v[246:247] neg_lo:[0,0,1] neg_hi:[0,0,1]
	v_pk_fma_f32 v[68:69], v[68:69], v[144:145], v[238:239]
	v_pk_mul_f32 v[248:249], v[70:71], v[240:241]
	v_pk_mul_f32 v[240:241], v[78:79], v[240:241]
	v_pk_fma_f32 v[78:79], v[78:79], v[146:147], v[248:249] neg_lo:[0,0,1] neg_hi:[0,0,1]
	v_pk_fma_f32 v[70:71], v[70:71], v[146:147], v[240:241]
	v_pk_mul_f32 v[246:247], v[64:65], v[242:243]
	v_pk_mul_f32 v[242:243], v[72:73], v[242:243]
	v_pk_fma_f32 v[72:73], v[72:73], v[156:157], v[246:247] neg_lo:[0,0,1] neg_hi:[0,0,1]
	v_pk_fma_f32 v[64:65], v[64:65], v[156:157], v[242:243]
	v_pk_mul_f32 v[248:249], v[66:67], v[244:245]
	v_pk_mul_f32 v[244:245], v[74:75], v[244:245]
	v_pk_fma_f32 v[74:75], v[74:75], v[158:159], v[248:249] neg_lo:[0,0,1] neg_hi:[0,0,1]
	v_pk_fma_f32 v[66:67], v[66:67], v[158:159], v[244:245]
	v_pk_mul_f32 v[76:77], v[250:251], v[76:77] op_sel:[1,0] op_sel_hi:[1,1]
	v_pk_mul_f32 v[78:79], v[250:251], v[78:79] op_sel:[1,0] op_sel_hi:[1,1]
	v_pk_mul_f32 v[72:73], v[250:251], v[72:73] op_sel:[1,0] op_sel_hi:[1,1]
	v_pk_mul_f32 v[74:75], v[250:251], v[74:75] op_sel:[1,0] op_sel_hi:[1,1]
	v_pk_mul_f32 v[68:69], v[250:251], v[68:69] op_sel:[1,0] op_sel_hi:[1,1]
	v_pk_mul_f32 v[70:71], v[250:251], v[70:71] op_sel:[1,0] op_sel_hi:[1,1]
	v_pk_mul_f32 v[64:65], v[250:251], v[64:65] op_sel:[1,0] op_sel_hi:[1,1]
	v_pk_mul_f32 v[66:67], v[250:251], v[66:67] op_sel:[1,0] op_sel_hi:[1,1]
	v_cvt_pk_bf16_f32 v144, v76, v77
	v_cvt_pk_bf16_f32 v145, v78, v79
	v_cvt_pk_bf16_f32 v146, v72, v73
	v_cvt_pk_bf16_f32 v147, v74, v75
	v_cvt_pk_bf16_f32 v156, v68, v69
	v_cvt_pk_bf16_f32 v157, v70, v71
	v_cvt_pk_bf16_f32 v158, v64, v65
	v_cvt_pk_bf16_f32 v159, v66, v67
	v_add_u32_e32 v246, 0x90000, v196
	global_store_dwordx4 v246, v[144:147], s[66:67] sc1
	global_store_dwordx4 v246, v[156:159], s[66:67] offset:64 sc1
	v_or_b32_e32 v162, 0x5800, v197
	v_lshl_add_u64 v[198:199], v[138:139], 0, v[162:163]
	global_load_dwordx4 v[76:79], v[198:199], off
	global_load_dwordx4 v[72:75], v[198:199], off offset:16
	v_lshl_add_u64 v[198:199], v[136:137], 0, v[162:163]
	global_load_dwordx4 v[68:71], v[198:199], off
	global_load_dwordx4 v[64:67], v[198:199], off offset:16
	s_waitcnt lgkmcnt(0)
	v_mul_f32_e32 v250, s21, v250
	ds_read_b32 v251, v152 offset:576
	s_waitcnt vmcnt(18)
; __device__ __forceinline__ unsigned cvt_pk_bf16(float lo, float hi) { unsigned r; asm volatile("v_cvt_pk_bf16_f32 %0, %1, %2" : "=v"(r) : "v"(lo), "v"(hi)); return r; }
;     __device__ __forceinline__ void operator()(const f32x4 (&acc)[2][2][4][2], const Unit& u, int wr, int wc, int fr, int fq) const {
;     ...
;                 for (int m = 0; m < 4; ++m) { const int row = row0 + ai * HALF + m * 16; const int pos = row & 4095;
;                     const float rs = sc * rstd[row & 255];
;                     const f32x4 c0 = *(const f32x4*)(cosT + pos * 32 + 8 * fq), c1 = *(const f32x4*)(cosT + pos * 32 + 8 * fq + 4);
;                     const f32x4 s0 = *(const f32x4*)(sinT + pos * 32 + 8 * fq), s1 = *(const f32x4*)(sinT + pos * 32 + 8 * fq + 4);
;                     const f32x4 a0 = acc[ai][0][m][0], a1 = acc[ai][0][m][1], b0 = acc[ai][1][m][0], b1 = acc[ai][1][m][1];
;                     const f32x4 x0 = (a0 * c0 - b0 * s0) * rs, x1 = (a1 * c1 - b1 * s1) * rs, y0 = (b0 * c0 + a0 * s0) * rs, y1 = (b1 * c1 + a1 * s1) * rs;
;                     bf16_t* rowp = O + (size_t)row * ldc + col;
;                     u32x4 w; w.x = cvt_pk_bf16(x0[0], x0[1]); w.y = cvt_pk_bf16(x0[2], x0[3]); w.z = cvt_pk_bf16(x1[0], x1[1]); w.w = cvt_pk_bf16(x1[2], x1[3]);
;                     *(u32x4*)rowp = w;
;                     w.x = cvt_pk_bf16(y0[0], y0[1]); w.y = cvt_pk_bf16(y0[2], y0[3]); w.z = cvt_pk_bf16(y1[0], y1[1]); w.w = cvt_pk_bf16(y1[2], y1[3]);
;                     *(u32x4*)(rowp + 32) = w; }
	v_pk_mul_f32 v[246:247], v[52:53], v[124:125]
	v_pk_mul_f32 v[124:125], v[60:61], v[124:125]
	v_pk_fma_f32 v[60:61], v[60:61], v[116:117], v[246:247] neg_lo:[0,0,1] neg_hi:[0,0,1]
	v_pk_fma_f32 v[52:53], v[52:53], v[116:117], v[124:125]
	v_pk_mul_f32 v[248:249], v[54:55], v[126:127]
	v_pk_mul_f32 v[126:127], v[62:63], v[126:127]
	v_pk_fma_f32 v[62:63], v[62:63], v[118:119], v[248:249] neg_lo:[0,0,1] neg_hi:[0,0,1]
	v_pk_fma_f32 v[54:55], v[54:55], v[118:119], v[126:127]
	v_pk_mul_f32 v[246:247], v[48:49], v[120:121]
	v_pk_mul_f32 v[120:121], v[56:57], v[120:121]
	v_pk_fma_f32 v[56:57], v[56:57], v[112:113], v[246:247] neg_lo:[0,0,1] neg_hi:[0,0,1]
	v_pk_fma_f32 v[48:49], v[48:49], v[112:113], v[120:121]
	v_pk_mul_f32 v[248:249], v[50:51], v[122:123]
	v_pk_mul_f32 v[122:123], v[58:59], v[122:123]
	v_pk_fma_f32 v[58:59], v[58:59], v[114:115], v[248:249] neg_lo:[0,0,1] neg_hi:[0,0,1]
	v_pk_fma_f32 v[50:51], v[50:51], v[114:115], v[122:123]
	v_pk_mul_f32 v[60:61], v[250:251], v[60:61] op_sel_hi:[0,1]
	v_pk_mul_f32 v[62:63], v[250:251], v[62:63] op_sel_hi:[0,1]
	v_pk_mul_f32 v[56:57], v[250:251], v[56:57] op_sel_hi:[0,1]
	v_pk_mul_f32 v[58:59], v[250:251], v[58:59] op_sel_hi:[0,1]
	v_pk_mul_f32 v[52:53], v[250:251], v[52:53] op_sel_hi:[0,1]
	v_pk_mul_f32 v[54:55], v[250:251], v[54:55] op_sel_hi:[0,1]
	v_pk_mul_f32 v[48:49], v[250:251], v[48:49] op_sel_hi:[0,1]
	v_pk_mul_f32 v[50:51], v[250:251], v[50:51] op_sel_hi:[0,1]
	v_cvt_pk_bf16_f32 v116, v60, v61
	v_cvt_pk_bf16_f32 v117, v62, v63
	v_cvt_pk_bf16_f32 v118, v56, v57
	v_cvt_pk_bf16_f32 v119, v58, v59
	v_cvt_pk_bf16_f32 v112, v52, v53
	v_cvt_pk_bf16_f32 v113, v54, v55
	v_cvt_pk_bf16_f32 v114, v48, v49
	v_cvt_pk_bf16_f32 v115, v50, v51
	v_add_u32_e32 v246, 0x180000, v196
	global_store_dwordx4 v246, v[116:119], s[66:67] sc1
	global_store_dwordx4 v246, v[112:115], s[66:67] offset:64 sc1
	s_waitcnt lgkmcnt(0)
	v_mul_f32_e32 v251, s21, v251
	ds_read_b32 v250, v152 offset:640
	s_waitcnt vmcnt(14)
	v_pk_mul_f32 v[246:247], v[36:37], v[108:109]
	v_pk_mul_f32 v[108:109], v[44:45], v[108:109]
	v_pk_fma_f32 v[44:45], v[44:45], v[100:101], v[246:247] neg_lo:[0,0,1] neg_hi:[0,0,1]
	v_pk_fma_f32 v[36:37], v[36:37], v[100:101], v[108:109]
	v_pk_mul_f32 v[248:249], v[38:39], v[110:111]
	v_pk_mul_f32 v[110:111], v[46:47], v[110:111]
	v_pk_fma_f32 v[46:47], v[46:47], v[102:103], v[248:249] neg_lo:[0,0,1] neg_hi:[0,0,1]
	v_pk_fma_f32 v[38:39], v[38:39], v[102:103], v[110:111]
	v_pk_mul_f32 v[246:247], v[32:33], v[104:105]
	v_pk_mul_f32 v[104:105], v[40:41], v[104:105]
	v_pk_fma_f32 v[40:41], v[40:41], v[96:97], v[246:247] neg_lo:[0,0,1] neg_hi:[0,0,1]
	v_pk_fma_f32 v[32:33], v[32:33], v[96:97], v[104:105]
	v_pk_mul_f32 v[248:249], v[34:35], v[106:107]
	v_pk_mul_f32 v[106:107], v[42:43], v[106:107]
	v_pk_fma_f32 v[42:43], v[42:43], v[98:99], v[248:249] neg_lo:[0,0,1] neg_hi:[0,0,1]
	v_pk_fma_f32 v[34:35], v[34:35], v[98:99], v[106:107]
	v_pk_mul_f32 v[44:45], v[250:251], v[44:45] op_sel:[1,0] op_sel_hi:[1,1]
	v_pk_mul_f32 v[46:47], v[250:251], v[46:47] op_sel:[1,0] op_sel_hi:[1,1]
	v_pk_mul_f32 v[40:41], v[250:251], v[40:41] op_sel:[1,0] op_sel_hi:[1,1]
	v_pk_mul_f32 v[42:43], v[250:251], v[42:43] op_sel:[1,0] op_sel_hi:[1,1]
	v_pk_mul_f32 v[36:37], v[250:251], v[36:37] op_sel:[1,0] op_sel_hi:[1,1]
	v_pk_mul_f32 v[38:39], v[250:251], v[38:39] op_sel:[1,0] op_sel_hi:[1,1]
	v_pk_mul_f32 v[32:33], v[250:251], v[32:33] op_sel:[1,0] op_sel_hi:[1,1]
	v_pk_mul_f32 v[34:35], v[250:251], v[34:35] op_sel:[1,0] op_sel_hi:[1,1]
	v_cvt_pk_bf16_f32 v100, v44, v45
	v_cvt_pk_bf16_f32 v101, v46, v47
	v_cvt_pk_bf16_f32 v102, v40, v41
	v_cvt_pk_bf16_f32 v103, v42, v43
	v_cvt_pk_bf16_f32 v96, v36, v37
	v_cvt_pk_bf16_f32 v97, v38, v39
	v_cvt_pk_bf16_f32 v98, v32, v33
	v_cvt_pk_bf16_f32 v99, v34, v35
	v_add_u32_e32 v246, 0x1b0000, v196
	global_store_dwordx4 v246, v[100:103], s[66:67] sc1
	global_store_dwordx4 v246, v[96:99], s[66:67] offset:64 sc1
	s_waitcnt lgkmcnt(0)
; __device__ __forceinline__ unsigned cvt_pk_bf16(float lo, float hi) { unsigned r; asm volatile("v_cvt_pk_bf16_f32 %0, %1, %2" : "=v"(r) : "v"(lo), "v"(hi)); return r; }
;     __device__ __forceinline__ void operator()(const f32x4 (&acc)[2][2][4][2], const Unit& u, int wr, int wc, int fr, int fq) const {
;     ...
;                 for (int m = 0; m < 4; ++m) { const int row = row0 + ai * HALF + m * 16; const int pos = row & 4095;
;                     const float rs = sc * rstd[row & 255];
;                     const f32x4 c0 = *(const f32x4*)(cosT + pos * 32 + 8 * fq), c1 = *(const f32x4*)(cosT + pos * 32 + 8 * fq + 4);
;                     const f32x4 s0 = *(const f32x4*)(sinT + pos * 32 + 8 * fq), s1 = *(const f32x4*)(sinT + pos * 32 + 8 * fq + 4);
;                     const f32x4 a0 = acc[ai][0][m][0], a1 = acc[ai][0][m][1], b0 = acc[ai][1][m][0], b1 = acc[ai][1][m][1];
;                     const f32x4 x0 = (a0 * c0 - b0 * s0) * rs, x1 = (a1 * c1 - b1 * s1) * rs, y0 = (b0 * c0 + a0 * s0) * rs, y1 = (b1 * c1 + a1 * s1) * rs;
;                     bf16_t* rowp = O + (size_t)row * ldc + col;
;                     u32x4 w; w.x = cvt_pk_bf16(x0[0], x0[1]); w.y = cvt_pk_bf16(x0[2], x0[3]); w.z = cvt_pk_bf16(x1[0], x1[1]); w.w = cvt_pk_bf16(x1[2], x1[3]);
;                     *(u32x4*)rowp = w;
;                     w.x = cvt_pk_bf16(y0[0], y0[1]); w.y = cvt_pk_bf16(y0[2], y0[3]); w.z = cvt_pk_bf16(y1[0], y1[1]); w.w = cvt_pk_bf16(y1[2], y1[3]);
;                     *(u32x4*)(rowp + 32) = w; }
	v_mul_f32_e32 v250, s21, v250
	ds_read_b32 v251, v152 offset:704
	s_waitcnt vmcnt(10)
	v_pk_mul_f32 v[246:247], v[20:21], v[92:93]
	v_pk_mul_f32 v[92:93], v[28:29], v[92:93]
	v_pk_fma_f32 v[28:29], v[28:29], v[84:85], v[246:247] neg_lo:[0,0,1] neg_hi:[0,0,1]
	v_pk_fma_f32 v[20:21], v[20:21], v[84:85], v[92:93]
	v_pk_mul_f32 v[248:249], v[22:23], v[94:95]
	v_pk_mul_f32 v[94:95], v[30:31], v[94:95]
	v_pk_fma_f32 v[30:31], v[30:31], v[86:87], v[248:249] neg_lo:[0,0,1] neg_hi:[0,0,1]
	v_pk_fma_f32 v[22:23], v[22:23], v[86:87], v[94:95]
	v_pk_mul_f32 v[246:247], v[16:17], v[88:89]
	v_pk_mul_f32 v[88:89], v[24:25], v[88:89]
	v_pk_fma_f32 v[24:25], v[24:25], v[80:81], v[246:247] neg_lo:[0,0,1] neg_hi:[0,0,1]
	v_pk_fma_f32 v[16:17], v[16:17], v[80:81], v[88:89]
	v_pk_mul_f32 v[248:249], v[18:19], v[90:91]
	v_pk_mul_f32 v[90:91], v[26:27], v[90:91]
	v_pk_fma_f32 v[26:27], v[26:27], v[82:83], v[248:249] neg_lo:[0,0,1] neg_hi:[0,0,1]
	v_pk_fma_f32 v[18:19], v[18:19], v[82:83], v[90:91]
	v_pk_mul_f32 v[28:29], v[250:251], v[28:29] op_sel_hi:[0,1]
	v_pk_mul_f32 v[30:31], v[250:251], v[30:31] op_sel_hi:[0,1]
	v_pk_mul_f32 v[24:25], v[250:251], v[24:25] op_sel_hi:[0,1]
	v_pk_mul_f32 v[26:27], v[250:251], v[26:27] op_sel_hi:[0,1]
	v_pk_mul_f32 v[20:21], v[250:251], v[20:21] op_sel_hi:[0,1]
	v_pk_mul_f32 v[22:23], v[250:251], v[22:23] op_sel_hi:[0,1]
	v_pk_mul_f32 v[16:17], v[250:251], v[16:17] op_sel_hi:[0,1]
	v_pk_mul_f32 v[18:19], v[250:251], v[18:19] op_sel_hi:[0,1]
	v_cvt_pk_bf16_f32 v84, v28, v29
	v_cvt_pk_bf16_f32 v85, v30, v31
	v_cvt_pk_bf16_f32 v86, v24, v25
	v_cvt_pk_bf16_f32 v87, v26, v27
	v_cvt_pk_bf16_f32 v80, v20, v21
	v_cvt_pk_bf16_f32 v81, v22, v23
	v_cvt_pk_bf16_f32 v82, v16, v17
	v_cvt_pk_bf16_f32 v83, v18, v19
	v_add_u32_e32 v246, 0x1e0000, v196
	global_store_dwordx4 v246, v[84:87], s[66:67] sc1
	global_store_dwordx4 v246, v[80:83], s[66:67] offset:64 sc1
	s_waitcnt lgkmcnt(0)
	v_mul_f32_e32 v251, s21, v251
	s_waitcnt vmcnt(6)
	v_pk_mul_f32 v[246:247], v[4:5], v[76:77]
	v_pk_mul_f32 v[76:77], v[12:13], v[76:77]
	v_pk_fma_f32 v[12:13], v[12:13], v[68:69], v[246:247] neg_lo:[0,0,1] neg_hi:[0,0,1]
	v_pk_fma_f32 v[4:5], v[4:5], v[68:69], v[76:77]
	v_pk_mul_f32 v[248:249], v[6:7], v[78:79]
	v_pk_mul_f32 v[78:79], v[14:15], v[78:79]
	v_pk_fma_f32 v[14:15], v[14:15], v[70:71], v[248:249] neg_lo:[0,0,1] neg_hi:[0,0,1]
	v_pk_fma_f32 v[6:7], v[6:7], v[70:71], v[78:79]
	v_pk_mul_f32 v[246:247], v[0:1], v[72:73]
	v_pk_mul_f32 v[72:73], v[8:9], v[72:73]
	v_pk_fma_f32 v[8:9], v[8:9], v[64:65], v[246:247] neg_lo:[0,0,1] neg_hi:[0,0,1]
	v_pk_fma_f32 v[0:1], v[0:1], v[64:65], v[72:73]
	v_pk_mul_f32 v[248:249], v[2:3], v[74:75]
	v_pk_mul_f32 v[74:75], v[10:11], v[74:75]
	v_pk_fma_f32 v[10:11], v[10:11], v[66:67], v[248:249] neg_lo:[0,0,1] neg_hi:[0,0,1]
	v_pk_fma_f32 v[2:3], v[2:3], v[66:67], v[74:75]
	v_pk_mul_f32 v[12:13], v[250:251], v[12:13] op_sel:[1,0] op_sel_hi:[1,1]
	v_pk_mul_f32 v[14:15], v[250:251], v[14:15] op_sel:[1,0] op_sel_hi:[1,1]
	v_pk_mul_f32 v[8:9], v[250:251], v[8:9] op_sel:[1,0] op_sel_hi:[1,1]
	v_pk_mul_f32 v[10:11], v[250:251], v[10:11] op_sel:[1,0] op_sel_hi:[1,1]
	v_pk_mul_f32 v[4:5], v[250:251], v[4:5] op_sel:[1,0] op_sel_hi:[1,1]
	v_pk_mul_f32 v[6:7], v[250:251], v[6:7] op_sel:[1,0] op_sel_hi:[1,1]
	v_pk_mul_f32 v[0:1], v[250:251], v[0:1] op_sel:[1,0] op_sel_hi:[1,1]
	v_pk_mul_f32 v[2:3], v[250:251], v[2:3] op_sel:[1,0] op_sel_hi:[1,1]
	v_cvt_pk_bf16_f32 v68, v12, v13
	v_cvt_pk_bf16_f32 v69, v14, v15
	v_cvt_pk_bf16_f32 v70, v8, v9
	v_cvt_pk_bf16_f32 v71, v10, v11
	v_cvt_pk_bf16_f32 v64, v4, v5
	v_cvt_pk_bf16_f32 v65, v6, v7
	v_cvt_pk_bf16_f32 v66, v0, v1
	v_cvt_pk_bf16_f32 v67, v2, v3
	v_add_u32_e32 v246, 0x210000, v196
	global_store_dwordx4 v246, v[68:71], s[66:67] sc1
	global_store_dwordx4 v246, v[64:67], s[66:67] offset:64 sc1
	s_andn2_b64 vcc, exec, s[38:39]
	s_mov_b64 s[20:21], -1
	s_cbranch_vccnz .LBB0_134
	s_branch .LBB0_150

; __device__ __forceinline__ unsigned cvt_pk_bf16(float lo, float hi) { unsigned r; asm volatile("v_cvt_pk_bf16_f32 %0, %1, %2" : "=v"(r) : "v"(lo), "v"(hi)); return r; }
;     __device__ __forceinline__ void operator()(const f32x4 (&acc)[2][2][4][2], const Unit& u, int wr, int wc, int fr, int fq) const {
;     ...
;         } else {
;             const int col0 = u.pn * BM + wc * 32 + 8 * fq;
; #pragma unroll
;             for (int ai = 0; ai < 2; ++ai)
; #pragma unroll
;                 for (int m = 0; m < 4; ++m) { const int row = row0 + ai * HALF + m * 16; bf16_t* rowp = O + (size_t)row * ldc + col0;
;                     const float rs = rstd[row & 255];
; #pragma unroll
;                     for (int bj = 0; bj < 2; ++bj) { const f32x4 v0 = acc[ai][bj][m][0] * rs, v1 = acc[ai][bj][m][1] * rs;
;                         u32x4 w; w.x = cvt_pk_bf16(v0[0], v0[1]); w.y = cvt_pk_bf16(v0[2], v0[3]); w.z = cvt_pk_bf16(v1[0], v1[1]); w.w = cvt_pk_bf16(v1[2], v1[3]);
;                         *(u32x4*)(rowp + bj * HALF) = w; } }
.LBB0_144:
	s_cmp_lt_u32 s76, 16
	s_cbranch_scc0 .LBB0_146
	ds_read_b32 v146, v152
	v_mov_b64_e32 v[144:145], s[66:67]
	v_lshlrev_b32_e32 v147, 1, v150
	v_mad_i64_i32 v[156:157], s[20:21], v155, s1, v[144:145]
	v_lshl_or_b32 v162, s76, 9, v147
	v_lshl_add_u64 v[174:175], v[156:157], 0, v[162:163]
	s_waitcnt lgkmcnt(0)
	v_pk_mul_f32 v[158:159], v[126:127], v[146:147] op_sel_hi:[1,0]
	v_pk_mul_f32 v[156:157], v[124:125], v[146:147] op_sel_hi:[1,0]
	v_pk_mul_f32 v[176:177], v[122:123], v[146:147] op_sel_hi:[1,0]
	v_pk_mul_f32 v[178:179], v[120:121], v[146:147] op_sel_hi:[1,0]
	v_cvt_pk_bf16_f32 v156, v156, v157
	v_cvt_pk_bf16_f32 v157, v158, v159
	s_nop 0
	v_cvt_pk_bf16_f32 v158, v178, v179
	v_cvt_pk_bf16_f32 v159, v176, v177
	global_store_dwordx4 v[174:175], v[156:159], off sc1
	v_pk_mul_f32 v[176:177], v[114:115], v[146:147] op_sel_hi:[1,0]
	s_nop 0
	v_pk_mul_f32 v[158:159], v[118:119], v[146:147] op_sel_hi:[1,0]
	v_pk_mul_f32 v[156:157], v[116:117], v[146:147] op_sel_hi:[1,0]
	v_pk_mul_f32 v[146:147], v[112:113], v[146:147] op_sel_hi:[1,0]
	v_cvt_pk_bf16_f32 v156, v156, v157
	v_cvt_pk_bf16_f32 v157, v158, v159
	s_nop 0
	v_cvt_pk_bf16_f32 v158, v146, v147
	v_bitop3_b32 v146, v155, s57, 16 bitop3:0xc8
	v_lshl_add_u32 v146, v146, 2, s74
	v_cvt_pk_bf16_f32 v159, v176, v177
	ds_read_b32 v146, v146
	v_or_b32_e32 v147, 16, v155
	global_store_dwordx4 v[174:175], v[156:159], off offset:256 sc1
	s_waitcnt lgkmcnt(0)
	v_pk_mul_f32 v[176:177], v[106:107], v[146:147] op_sel_hi:[1,0]
	v_mad_i64_i32 v[156:157], s[20:21], v147, s1, v[144:145]
	v_lshl_add_u64 v[174:175], v[156:157], 0, v[162:163]
	v_pk_mul_f32 v[158:159], v[110:111], v[146:147] op_sel_hi:[1,0]
	v_pk_mul_f32 v[156:157], v[108:109], v[146:147] op_sel_hi:[1,0]
	v_pk_mul_f32 v[178:179], v[104:105], v[146:147] op_sel_hi:[1,0]
	v_cvt_pk_bf16_f32 v156, v156, v157
	v_cvt_pk_bf16_f32 v157, v158, v159
	s_nop 0
	v_cvt_pk_bf16_f32 v158, v178, v179
	v_cvt_pk_bf16_f32 v159, v176, v177
	global_store_dwordx4 v[174:175], v[156:159], off sc1
	v_pk_mul_f32 v[176:177], v[98:99], v[146:147] op_sel_hi:[1,0]
	s_nop 0
	v_pk_mul_f32 v[158:159], v[102:103], v[146:147] op_sel_hi:[1,0]
	v_pk_mul_f32 v[156:157], v[100:101], v[146:147] op_sel_hi:[1,0]
	v_pk_mul_f32 v[146:147], v[96:97], v[146:147] op_sel_hi:[1,0]
	v_cvt_pk_bf16_f32 v156, v156, v157
	v_cvt_pk_bf16_f32 v157, v158, v159
	s_nop 0
	v_cvt_pk_bf16_f32 v158, v146, v147
	v_bitop3_b32 v146, v155, s7, 32 bitop3:0xc8
	v_lshl_add_u32 v146, v146, 2, s74
	v_cvt_pk_bf16_f32 v159, v176, v177
	ds_read_b32 v146, v146
	v_or_b32_e32 v147, 32, v155
	global_store_dwordx4 v[174:175], v[156:159], off offset:256 sc1
	s_waitcnt lgkmcnt(0)
	v_pk_mul_f32 v[176:177], v[90:91], v[146:147] op_sel_hi:[1,0]
	v_mad_i64_i32 v[156:157], s[20:21], v147, s1, v[144:145]
	v_lshl_add_u64 v[174:175], v[156:157], 0, v[162:163]
	v_pk_mul_f32 v[158:159], v[94:95], v[146:147] op_sel_hi:[1,0]
	v_pk_mul_f32 v[156:157], v[92:93], v[146:147] op_sel_hi:[1,0]
	v_pk_mul_f32 v[178:179], v[88:89], v[146:147] op_sel_hi:[1,0]
	v_cvt_pk_bf16_f32 v156, v156, v157
	v_cvt_pk_bf16_f32 v157, v158, v159
	s_nop 0
	v_cvt_pk_bf16_f32 v158, v178, v179
	v_cvt_pk_bf16_f32 v159, v176, v177
	global_store_dwordx4 v[174:175], v[156:159], off sc1
	v_pk_mul_f32 v[176:177], v[82:83], v[146:147] op_sel_hi:[1,0]
	s_nop 0
	v_pk_mul_f32 v[158:159], v[86:87], v[146:147] op_sel_hi:[1,0]
	v_pk_mul_f32 v[156:157], v[84:85], v[146:147] op_sel_hi:[1,0]
	v_pk_mul_f32 v[146:147], v[80:81], v[146:147] op_sel_hi:[1,0]
	v_cvt_pk_bf16_f32 v156, v156, v157
	v_cvt_pk_bf16_f32 v157, v158, v159
	s_nop 0
	v_cvt_pk_bf16_f32 v158, v146, v147
	v_bitop3_b32 v146, v155, s63, 48 bitop3:0xc8
	v_lshl_add_u32 v146, v146, 2, s74
	v_cvt_pk_bf16_f32 v159, v176, v177
	ds_read_b32 v146, v146
	v_or_b32_e32 v147, 48, v155
	global_store_dwordx4 v[174:175], v[156:159], off offset:256 sc1
	s_waitcnt lgkmcnt(0)
	v_pk_mul_f32 v[176:177], v[74:75], v[146:147] op_sel_hi:[1,0]
	v_mad_i64_i32 v[156:157], s[20:21], v147, s1, v[144:145]
	v_lshl_add_u64 v[174:175], v[156:157], 0, v[162:163]
	v_pk_mul_f32 v[158:159], v[78:79], v[146:147] op_sel_hi:[1,0]
	v_pk_mul_f32 v[156:157], v[76:77], v[146:147] op_sel_hi:[1,0]
	v_pk_mul_f32 v[178:179], v[72:73], v[146:147] op_sel_hi:[1,0]
	v_cvt_pk_bf16_f32 v156, v156, v157
	v_cvt_pk_bf16_f32 v157, v158, v159
	s_nop 0
	v_cvt_pk_bf16_f32 v158, v178, v179
	v_cvt_pk_bf16_f32 v159, v176, v177
	global_store_dwordx4 v[174:175], v[156:159], off sc1
	v_pk_mul_f32 v[176:177], v[66:67], v[146:147] op_sel_hi:[1,0]
	s_nop 0
	v_pk_mul_f32 v[158:159], v[70:71], v[146:147] op_sel_hi:[1,0]
	v_pk_mul_f32 v[156:157], v[68:69], v[146:147] op_sel_hi:[1,0]
	v_pk_mul_f32 v[146:147], v[64:65], v[146:147] op_sel_hi:[1,0]
	v_cvt_pk_bf16_f32 v156, v156, v157
	v_cvt_pk_bf16_f32 v157, v158, v159
	s_nop 0
	v_cvt_pk_bf16_f32 v158, v146, v147
	v_add_u32_e32 v147, 0x80, v155
	v_and_b32_e32 v146, 0xcf, v147
	v_lshl_add_u32 v146, v146, 2, s74
	v_cvt_pk_bf16_f32 v159, v176, v177
	ds_read_b32 v146, v146
	global_store_dwordx4 v[174:175], v[156:159], off offset:256 sc1
	s_waitcnt lgkmcnt(0)
; __device__ __forceinline__ unsigned cvt_pk_bf16(float lo, float hi) { unsigned r; asm volatile("v_cvt_pk_bf16_f32 %0, %1, %2" : "=v"(r) : "v"(lo), "v"(hi)); return r; }
;     __device__ __forceinline__ void operator()(const f32x4 (&acc)[2][2][4][2], const Unit& u, int wr, int wc, int fr, int fq) const {
;     ...
;             for (int ai = 0; ai < 2; ++ai)
; #pragma unroll
;                 for (int m = 0; m < 4; ++m) { const int row = row0 + ai * HALF + m * 16; bf16_t* rowp = O + (size_t)row * ldc + col0;
;                     const float rs = rstd[row & 255];
; #pragma unroll
;                     for (int bj = 0; bj < 2; ++bj) { const f32x4 v0 = acc[ai][bj][m][0] * rs, v1 = acc[ai][bj][m][1] * rs;
;                         u32x4 w; w.x = cvt_pk_bf16(v0[0], v0[1]); w.y = cvt_pk_bf16(v0[2], v0[3]); w.z = cvt_pk_bf16(v1[0], v1[1]); w.w = cvt_pk_bf16(v1[2], v1[3]);
;                         *(u32x4*)(rowp + bj * HALF) = w; } }
	v_pk_mul_f32 v[176:177], v[58:59], v[146:147] op_sel_hi:[1,0]
	v_mad_i64_i32 v[156:157], s[20:21], v147, s1, v[144:145]
	v_lshl_add_u64 v[174:175], v[156:157], 0, v[162:163]
	v_pk_mul_f32 v[158:159], v[62:63], v[146:147] op_sel_hi:[1,0]
	v_pk_mul_f32 v[156:157], v[60:61], v[146:147] op_sel_hi:[1,0]
	v_pk_mul_f32 v[178:179], v[56:57], v[146:147] op_sel_hi:[1,0]
	v_cvt_pk_bf16_f32 v156, v156, v157
	v_cvt_pk_bf16_f32 v157, v158, v159
	s_nop 0
	v_cvt_pk_bf16_f32 v158, v178, v179
	v_cvt_pk_bf16_f32 v159, v176, v177
	global_store_dwordx4 v[174:175], v[156:159], off sc1
	v_pk_mul_f32 v[176:177], v[50:51], v[146:147] op_sel_hi:[1,0]
	s_nop 0
	v_pk_mul_f32 v[158:159], v[54:55], v[146:147] op_sel_hi:[1,0]
	v_pk_mul_f32 v[156:157], v[52:53], v[146:147] op_sel_hi:[1,0]
	v_pk_mul_f32 v[146:147], v[48:49], v[146:147] op_sel_hi:[1,0]
	v_cvt_pk_bf16_f32 v156, v156, v157
	v_cvt_pk_bf16_f32 v157, v158, v159
	s_nop 0
	v_cvt_pk_bf16_f32 v158, v146, v147
	v_add_u32_e32 v147, 0x90, v155
	v_and_b32_e32 v146, 0xdf, v147
	v_lshl_add_u32 v146, v146, 2, s74
	v_cvt_pk_bf16_f32 v159, v176, v177
	ds_read_b32 v146, v146
	global_store_dwordx4 v[174:175], v[156:159], off offset:256 sc1
	s_waitcnt lgkmcnt(0)
	v_pk_mul_f32 v[176:177], v[42:43], v[146:147] op_sel_hi:[1,0]
	v_mad_i64_i32 v[156:157], s[20:21], v147, s1, v[144:145]
	v_lshl_add_u64 v[174:175], v[156:157], 0, v[162:163]
	v_pk_mul_f32 v[158:159], v[46:47], v[146:147] op_sel_hi:[1,0]
	v_pk_mul_f32 v[156:157], v[44:45], v[146:147] op_sel_hi:[1,0]
	v_pk_mul_f32 v[178:179], v[40:41], v[146:147] op_sel_hi:[1,0]
	v_cvt_pk_bf16_f32 v156, v156, v157
	v_cvt_pk_bf16_f32 v157, v158, v159
	s_nop 0
	v_cvt_pk_bf16_f32 v158, v178, v179
	v_cvt_pk_bf16_f32 v159, v176, v177
	global_store_dwordx4 v[174:175], v[156:159], off sc1
	v_pk_mul_f32 v[176:177], v[34:35], v[146:147] op_sel_hi:[1,0]
	s_nop 0
	v_pk_mul_f32 v[158:159], v[38:39], v[146:147] op_sel_hi:[1,0]
	v_pk_mul_f32 v[156:157], v[36:37], v[146:147] op_sel_hi:[1,0]
	v_pk_mul_f32 v[146:147], v[32:33], v[146:147] op_sel_hi:[1,0]
	v_cvt_pk_bf16_f32 v156, v156, v157
	v_cvt_pk_bf16_f32 v157, v158, v159
	s_nop 0
	v_cvt_pk_bf16_f32 v158, v146, v147
	v_add_u32_e32 v147, 0xa0, v155
	v_and_b32_e32 v146, 0xef, v147
	v_lshl_add_u32 v146, v146, 2, s74
	v_cvt_pk_bf16_f32 v159, v176, v177
	ds_read_b32 v146, v146
	global_store_dwordx4 v[174:175], v[156:159], off offset:256 sc1
	s_waitcnt lgkmcnt(0)
	v_pk_mul_f32 v[176:177], v[26:27], v[146:147] op_sel_hi:[1,0]
	v_mad_i64_i32 v[156:157], s[20:21], v147, s1, v[144:145]
	v_lshl_add_u64 v[174:175], v[156:157], 0, v[162:163]
	v_pk_mul_f32 v[158:159], v[30:31], v[146:147] op_sel_hi:[1,0]
	v_pk_mul_f32 v[156:157], v[28:29], v[146:147] op_sel_hi:[1,0]
	v_pk_mul_f32 v[178:179], v[24:25], v[146:147] op_sel_hi:[1,0]
	v_cvt_pk_bf16_f32 v156, v156, v157
	v_cvt_pk_bf16_f32 v157, v158, v159
	s_nop 0
	v_cvt_pk_bf16_f32 v158, v178, v179
	v_cvt_pk_bf16_f32 v159, v176, v177
	global_store_dwordx4 v[174:175], v[156:159], off sc1
	v_pk_mul_f32 v[176:177], v[18:19], v[146:147] op_sel_hi:[1,0]
	s_nop 0
	v_pk_mul_f32 v[158:159], v[22:23], v[146:147] op_sel_hi:[1,0]
	v_pk_mul_f32 v[156:157], v[20:21], v[146:147] op_sel_hi:[1,0]
	v_pk_mul_f32 v[146:147], v[16:17], v[146:147] op_sel_hi:[1,0]
	v_cvt_pk_bf16_f32 v156, v156, v157
	v_cvt_pk_bf16_f32 v157, v158, v159
	s_nop 0
	v_cvt_pk_bf16_f32 v158, v146, v147
	v_add_u32_e32 v146, 0xb0, v155
	v_and_b32_e32 v147, 0xff, v146
	v_lshl_add_u32 v147, v147, 2, s74
	v_cvt_pk_bf16_f32 v159, v176, v177
	ds_read_b32 v176, v147
	v_mad_i64_i32 v[144:145], s[20:21], v146, s1, v[144:145]
	global_store_dwordx4 v[174:175], v[156:159], off offset:256 sc1
	s_mov_b64 s[20:21], 0
	s_waitcnt lgkmcnt(0)
	v_pk_mul_f32 v[146:147], v[14:15], v[176:177] op_sel_hi:[1,0]
	v_lshl_add_u64 v[156:157], v[144:145], 0, v[162:163]
	v_pk_mul_f32 v[144:145], v[12:13], v[176:177] op_sel_hi:[1,0]
	v_pk_mul_f32 v[158:159], v[10:11], v[176:177] op_sel_hi:[1,0]
	v_pk_mul_f32 v[174:175], v[8:9], v[176:177] op_sel_hi:[1,0]
	v_cvt_pk_bf16_f32 v144, v144, v145
	v_cvt_pk_bf16_f32 v145, v146, v147
	s_nop 0
	v_cvt_pk_bf16_f32 v146, v174, v175
	v_cvt_pk_bf16_f32 v147, v158, v159
	global_store_dwordx4 v[156:157], v[144:147], off sc1
	v_pk_mul_f32 v[158:159], v[2:3], v[176:177] op_sel_hi:[1,0]
	v_pk_mul_f32 v[174:175], v[0:1], v[176:177] op_sel_hi:[1,0]
	v_pk_mul_f32 v[146:147], v[6:7], v[176:177] op_sel_hi:[1,0]
	v_pk_mul_f32 v[144:145], v[4:5], v[176:177] op_sel_hi:[1,0]
	s_nop 0
	v_cvt_pk_bf16_f32 v144, v144, v145
	v_cvt_pk_bf16_f32 v145, v146, v147
	v_cvt_pk_bf16_f32 v146, v174, v175
	v_cvt_pk_bf16_f32 v147, v158, v159
	global_store_dwordx4 v[156:157], v[144:147], off offset:256 sc1
; __device__ __forceinline__ unsigned cvt_pk_bf16(float lo, float hi) { unsigned r; asm volatile("v_cvt_pk_bf16_f32 %0, %1, %2" : "=v"(r) : "v"(lo), "v"(hi)); return r; }
;     __device__ __forceinline__ void operator()(const f32x4 (&acc)[2][2][4][2], const Unit& u, int wr, int wc, int fr, int fq) const {
;     ...
;         } else if (u.pn >= 16) {
;             const int col0 = 4096 + (u.pn - 16) * HALF + wc * 32 + 8 * fq;
; #pragma unroll
;             for (int ai = 0; ai < 2; ++ai)
; #pragma unroll
;                 for (int m = 0; m < 4; ++m) { const int row = row0 + ai * HALF + m * 16; const float rs = rstd[row & 255], rs2 = rs * rs;
;                     const f32x4 z0 = acc[ai][0][m][0] * acc[ai][1][m][0] * rs2, z1 = acc[ai][0][m][1] * acc[ai][1][m][1] * rs2;
;                     u32x4 w; w.x = cvt_pk_bf16(z0[0], z0[1]); w.y = cvt_pk_bf16(z0[2], z0[3]); w.z = cvt_pk_bf16(z1[0], z1[1]); w.w = cvt_pk_bf16(z1[2], z1[3]);
;                     *(u32x4*)(O + (size_t)row * ldc + col0) = w; }
.LBB0_146:
	s_andn2_b64 vcc, exec, s[20:21]
	s_cbranch_vccnz .LBB0_148
	ds_read_b32 v156, v152
	v_pk_mul_f32 v[158:159], v[122:123], v[114:115]
	v_pk_mul_f32 v[174:175], v[120:121], v[112:113]
	v_bitop3_b32 v162, v155, s57, 16 bitop3:0xc8
	v_pk_mul_f32 v[144:145], v[126:127], v[118:119]
	s_waitcnt lgkmcnt(0)
	v_mul_f32_e32 v156, v156, v156
	v_pk_mul_f32 v[146:147], v[124:125], v[116:117]
	v_pk_mul_f32 v[176:177], v[158:159], v[156:157] op_sel_hi:[1,0]
	v_pk_mul_f32 v[158:159], v[174:175], v[156:157] op_sel_hi:[1,0]
	v_lshl_add_u32 v162, v162, 2, s74
	v_pk_mul_f32 v[144:145], v[144:145], v[156:157] op_sel_hi:[1,0]
	v_pk_mul_f32 v[146:147], v[146:147], v[156:157] op_sel_hi:[1,0]
	s_lshl_b32 s28, s76, 7
	v_cvt_pk_bf16_f32 v156, v146, v147
	v_cvt_pk_bf16_f32 v157, v144, v145
	v_cvt_pk_bf16_f32 v158, v158, v159
	v_cvt_pk_bf16_f32 v159, v176, v177
	ds_read_b32 v174, v162
	v_mov_b64_e32 v[144:145], s[66:67]
	v_mad_i64_i32 v[146:147], s[20:21], v155, s1, v[144:145]
	v_add_lshl_u32 v162, v151, s28, 1
	v_lshl_add_u64 v[146:147], v[146:147], 0, v[162:163]
	global_store_dwordx4 v[146:147], v[156:159], off sc1
	s_waitcnt lgkmcnt(0)
	v_mul_f32_e32 v146, v174, v174
	v_pk_mul_f32 v[176:177], v[104:105], v[96:97]
	v_pk_mul_f32 v[156:157], v[110:111], v[102:103]
	v_pk_mul_f32 v[158:159], v[108:109], v[100:101]
	v_pk_mul_f32 v[174:175], v[156:157], v[146:147] op_sel_hi:[1,0]
	v_pk_mul_f32 v[156:157], v[158:159], v[146:147] op_sel_hi:[1,0]
	v_pk_mul_f32 v[158:159], v[106:107], v[98:99]
	v_cvt_pk_bf16_f32 v156, v156, v157
	v_cvt_pk_bf16_f32 v157, v174, v175
	v_or_b32_e32 v180, 16, v155
	v_pk_mul_f32 v[178:179], v[158:159], v[146:147] op_sel_hi:[1,0]
	v_pk_mul_f32 v[146:147], v[176:177], v[146:147] op_sel_hi:[1,0]
	v_pk_mul_f32 v[176:177], v[88:89], v[80:81]
	v_cvt_pk_bf16_f32 v158, v146, v147
	v_bitop3_b32 v146, v155, s7, 32 bitop3:0xc8
	v_lshl_add_u32 v146, v146, 2, s74
	v_cvt_pk_bf16_f32 v159, v178, v179
	ds_read_b32 v174, v146
	v_mad_i64_i32 v[146:147], s[20:21], v180, s1, v[144:145]
	v_lshl_add_u64 v[146:147], v[146:147], 0, v[162:163]
	global_store_dwordx4 v[146:147], v[156:159], off sc1
	s_waitcnt lgkmcnt(0)
	v_mul_f32_e32 v146, v174, v174
	v_or_b32_e32 v180, 32, v155
	v_pk_mul_f32 v[156:157], v[94:95], v[86:87]
	v_pk_mul_f32 v[158:159], v[92:93], v[84:85]
	v_pk_mul_f32 v[174:175], v[156:157], v[146:147] op_sel_hi:[1,0]
	v_pk_mul_f32 v[156:157], v[158:159], v[146:147] op_sel_hi:[1,0]
	v_pk_mul_f32 v[158:159], v[90:91], v[82:83]
	v_cvt_pk_bf16_f32 v156, v156, v157
	v_cvt_pk_bf16_f32 v157, v174, v175
	v_add_u32_e32 v181, 0x80, v155
	v_pk_mul_f32 v[178:179], v[158:159], v[146:147] op_sel_hi:[1,0]
	v_pk_mul_f32 v[146:147], v[176:177], v[146:147] op_sel_hi:[1,0]
	v_pk_mul_f32 v[176:177], v[72:73], v[64:65]
	v_cvt_pk_bf16_f32 v158, v146, v147
	v_bitop3_b32 v146, v155, s63, 48 bitop3:0xc8
	v_lshl_add_u32 v146, v146, 2, s74
	v_cvt_pk_bf16_f32 v159, v178, v179
	ds_read_b32 v174, v146
	v_mad_i64_i32 v[146:147], s[20:21], v180, s1, v[144:145]
	v_lshl_add_u64 v[146:147], v[146:147], 0, v[162:163]
	global_store_dwordx4 v[146:147], v[156:159], off sc1
	s_waitcnt lgkmcnt(0)
	v_mul_f32_e32 v146, v174, v174
	v_or_b32_e32 v180, 48, v155
	v_pk_mul_f32 v[156:157], v[78:79], v[70:71]
	v_pk_mul_f32 v[158:159], v[76:77], v[68:69]
	v_pk_mul_f32 v[174:175], v[156:157], v[146:147] op_sel_hi:[1,0]
	v_pk_mul_f32 v[156:157], v[158:159], v[146:147] op_sel_hi:[1,0]
	v_pk_mul_f32 v[158:159], v[74:75], v[66:67]
	v_cvt_pk_bf16_f32 v156, v156, v157
	v_cvt_pk_bf16_f32 v157, v174, v175
	s_nop 0
	v_pk_mul_f32 v[178:179], v[158:159], v[146:147] op_sel_hi:[1,0]
	v_pk_mul_f32 v[146:147], v[176:177], v[146:147] op_sel_hi:[1,0]
	v_pk_mul_f32 v[176:177], v[56:57], v[48:49]
	v_cvt_pk_bf16_f32 v158, v146, v147
	v_and_b32_e32 v146, 0xcf, v181
	v_lshl_add_u32 v146, v146, 2, s74
	v_cvt_pk_bf16_f32 v159, v178, v179
	ds_read_b32 v174, v146
	v_mad_i64_i32 v[146:147], s[20:21], v180, s1, v[144:145]
	v_lshl_add_u64 v[146:147], v[146:147], 0, v[162:163]
	global_store_dwordx4 v[146:147], v[156:159], off sc1
	s_waitcnt lgkmcnt(0)
; __device__ __forceinline__ unsigned cvt_pk_bf16(float lo, float hi) { unsigned r; asm volatile("v_cvt_pk_bf16_f32 %0, %1, %2" : "=v"(r) : "v"(lo), "v"(hi)); return r; }
;     __device__ __forceinline__ void operator()(const f32x4 (&acc)[2][2][4][2], const Unit& u, int wr, int wc, int fr, int fq) const {
;     ...
;             for (int ai = 0; ai < 2; ++ai)
; #pragma unroll
;                 for (int m = 0; m < 4; ++m) { const int row = row0 + ai * HALF + m * 16; const float rs = rstd[row & 255], rs2 = rs * rs;
;                     const f32x4 z0 = acc[ai][0][m][0] * acc[ai][1][m][0] * rs2, z1 = acc[ai][0][m][1] * acc[ai][1][m][1] * rs2;
;                     u32x4 w; w.x = cvt_pk_bf16(z0[0], z0[1]); w.y = cvt_pk_bf16(z0[2], z0[3]); w.z = cvt_pk_bf16(z1[0], z1[1]); w.w = cvt_pk_bf16(z1[2], z1[3]);
;                     *(u32x4*)(O + (size_t)row * ldc + col0) = w; }
	v_mul_f32_e32 v146, v174, v174
	v_add_u32_e32 v180, 0x90, v155
	v_pk_mul_f32 v[156:157], v[62:63], v[54:55]
	v_pk_mul_f32 v[158:159], v[60:61], v[52:53]
	v_pk_mul_f32 v[174:175], v[156:157], v[146:147] op_sel_hi:[1,0]
	v_pk_mul_f32 v[156:157], v[158:159], v[146:147] op_sel_hi:[1,0]
	v_pk_mul_f32 v[158:159], v[58:59], v[50:51]
	v_cvt_pk_bf16_f32 v156, v156, v157
	v_cvt_pk_bf16_f32 v157, v174, v175
	s_nop 0
	v_pk_mul_f32 v[178:179], v[158:159], v[146:147] op_sel_hi:[1,0]
	v_pk_mul_f32 v[146:147], v[176:177], v[146:147] op_sel_hi:[1,0]
	v_pk_mul_f32 v[176:177], v[40:41], v[32:33]
	v_cvt_pk_bf16_f32 v158, v146, v147
	v_and_b32_e32 v146, 0xdf, v180
	v_lshl_add_u32 v146, v146, 2, s74
	v_cvt_pk_bf16_f32 v159, v178, v179
	ds_read_b32 v174, v146
	v_mad_i64_i32 v[146:147], s[20:21], v181, s1, v[144:145]
	v_lshl_add_u64 v[146:147], v[146:147], 0, v[162:163]
	global_store_dwordx4 v[146:147], v[156:159], off sc1
	s_waitcnt lgkmcnt(0)
	v_mul_f32_e32 v146, v174, v174
	v_add_u32_e32 v181, 0xa0, v155
	v_pk_mul_f32 v[156:157], v[46:47], v[38:39]
	v_pk_mul_f32 v[158:159], v[44:45], v[36:37]
	v_pk_mul_f32 v[174:175], v[156:157], v[146:147] op_sel_hi:[1,0]
	v_pk_mul_f32 v[156:157], v[158:159], v[146:147] op_sel_hi:[1,0]
	v_pk_mul_f32 v[158:159], v[42:43], v[34:35]
	v_cvt_pk_bf16_f32 v156, v156, v157
	v_cvt_pk_bf16_f32 v157, v174, v175
	s_nop 0
	v_pk_mul_f32 v[178:179], v[158:159], v[146:147] op_sel_hi:[1,0]
	v_pk_mul_f32 v[146:147], v[176:177], v[146:147] op_sel_hi:[1,0]
	v_pk_mul_f32 v[176:177], v[24:25], v[16:17]
	v_cvt_pk_bf16_f32 v158, v146, v147
	v_and_b32_e32 v146, 0xef, v181
	v_lshl_add_u32 v146, v146, 2, s74
	v_cvt_pk_bf16_f32 v159, v178, v179
	ds_read_b32 v174, v146
	v_mad_i64_i32 v[146:147], s[20:21], v180, s1, v[144:145]
	v_lshl_add_u64 v[146:147], v[146:147], 0, v[162:163]
	global_store_dwordx4 v[146:147], v[156:159], off sc1
	s_waitcnt lgkmcnt(0)
	v_mul_f32_e32 v146, v174, v174
	v_add_u32_e32 v180, 0xb0, v155
	v_pk_mul_f32 v[156:157], v[30:31], v[22:23]
	v_pk_mul_f32 v[158:159], v[28:29], v[20:21]
	v_pk_mul_f32 v[174:175], v[156:157], v[146:147] op_sel_hi:[1,0]
	v_pk_mul_f32 v[156:157], v[158:159], v[146:147] op_sel_hi:[1,0]
	v_pk_mul_f32 v[158:159], v[26:27], v[18:19]
	v_cvt_pk_bf16_f32 v156, v156, v157
	v_cvt_pk_bf16_f32 v157, v174, v175
	s_nop 0
	v_pk_mul_f32 v[178:179], v[158:159], v[146:147] op_sel_hi:[1,0]
	v_pk_mul_f32 v[146:147], v[176:177], v[146:147] op_sel_hi:[1,0]
	v_pk_mul_f32 v[176:177], v[8:9], v[0:1]
	v_cvt_pk_bf16_f32 v158, v146, v147
	v_and_b32_e32 v146, 0xff, v180
	v_lshl_add_u32 v146, v146, 2, s74
	v_cvt_pk_bf16_f32 v159, v178, v179
	ds_read_b32 v174, v146
	v_mad_i64_i32 v[146:147], s[20:21], v181, s1, v[144:145]
	v_lshl_add_u64 v[146:147], v[146:147], 0, v[162:163]
	global_store_dwordx4 v[146:147], v[156:159], off sc1
	s_waitcnt lgkmcnt(0)
	v_mul_f32_e32 v146, v174, v174
	v_mad_i64_i32 v[144:145], s[20:21], v180, s1, v[144:145]
	v_pk_mul_f32 v[156:157], v[14:15], v[6:7]
	v_pk_mul_f32 v[158:159], v[12:13], v[4:5]
	v_pk_mul_f32 v[174:175], v[156:157], v[146:147] op_sel_hi:[1,0]
	v_pk_mul_f32 v[156:157], v[158:159], v[146:147] op_sel_hi:[1,0]
	v_pk_mul_f32 v[158:159], v[10:11], v[2:3]
	v_lshl_add_u64 v[144:145], v[144:145], 0, v[162:163]
	v_pk_mul_f32 v[178:179], v[158:159], v[146:147] op_sel_hi:[1,0]
	v_pk_mul_f32 v[146:147], v[176:177], v[146:147] op_sel_hi:[1,0]
	v_cvt_pk_bf16_f32 v156, v156, v157
	v_cvt_pk_bf16_f32 v157, v174, v175
	s_nop 0
	v_cvt_pk_bf16_f32 v158, v146, v147
	v_cvt_pk_bf16_f32 v159, v178, v179
	global_store_dwordx4 v[144:145], v[156:159], off sc1

; __device__ __forceinline__ unsigned cvtpk(float lo, float hi) { f32x2_t v = {lo, hi}; bf16x2_t b = __builtin_convertvector(v, bf16x2_t); return __builtin_bit_cast(unsigned, b); }
; #define LDZ(row, z) do { const bf16x8 c_ = *reinterpret_cast<const bf16x8*>(proj + (long)(row) * LDP + 4096 + c8);     \
;     _Pragma("unroll") for (int e = 0; e < 8; ++e) z[e] = __uint_as_float(((unsigned)(unsigned short)c_[e]) << 16); } while (0)
; __device__ __forceinline__ void conv_tile(const bf16* __restrict__ proj, bf16* __restrict__ cat, const float* __restrict__ cw, long row0, int ch0, int lane) {
;   const int c8 = ch0 + (lane & 15) * 8; const long r0 = row0 + (lane >> 4) * 8;
;   float w0[8], w1[8], w2[8];
; #pragma unroll
;   for (int e = 0; e < 8; ++e) { w0[e] = cw[c8 + e]; w1[e] = cw[1024 + c8 + e]; w2[e] = cw[2048 + c8 + e]; }
;     ...
;   float zp[8], zc[8], zn[8];
;   if ((r0 & (SEQ - 1)) == 0) {
; #pragma unroll
;     for (int e = 0; e < 8; ++e) zp[e] = 0.f;
;   } else LDZ(r0 - 1, zp);
;   LDZ(r0, zc);
; #pragma unroll
;   for (int i = 0; i < 8; ++i) { const long row = r0 + i;
;     if (((row + 1) & (SEQ - 1)) == 0) {
; #pragma unroll
;       for (int e = 0; e < 8; ++e) zn[e] = 0.f;
;     } else LDZ(row + 1, zn);
;     const bf16x8 gb = *reinterpret_cast<const bf16x8*>(proj + row * LDP + 3072 + c8);
;     float y[8];
; #pragma unroll
;     for (int e = 0; e < 8; ++e) y[e] = __uint_as_float(((unsigned)(unsigned short)gb[e]) << 16) * (zp[e] * w0[e] + zc[e] * w1[e] + zn[e] * w2[e]);
;     u32x4 w; w.x = cvtpk(y[0], y[1]); w.y = cvtpk(y[2], y[3]); w.z = cvtpk(y[4], y[5]); w.w = cvtpk(y[6], y[7]);
;     *(u32x4*)(cat + row * LDC + 1024 + c8) = w;
.LBB0_242:
	s_cmpk_gt_u32 s31, 0xff
	s_mov_b64 s[20:21], -1
	s_waitcnt lgkmcnt(0)
	s_barrier
	s_cbranch_scc0 .LBB0_248
	v_and_b32_e32 v150, 0x78, v181
	v_and_b32_e32 v151, 24, v180
	v_or_b32_e32 v150, s28, v150
	v_or_b32_e32 v151, s44, v151
	v_lshlrev_b32_e32 v152, 2, v150
	v_mul_u32_u24_e32 v154, 0x3000, v151
	global_load_dwordx4 v[0:3], v152, s[42:43]
	global_load_dwordx4 v[4:7], v152, s[42:43] offset:16
	v_add_u32_e32 v153, 0x1000, v152
	v_lshlrev_b32_e32 v155, 1, v150
	global_load_dwordx4 v[8:11], v153, s[42:43]
	global_load_dwordx4 v[12:15], v153, s[42:43] offset:16
	v_add_u32_e32 v153, 0x2000, v152
	v_and_b32_e32 v159, 0xff8, v151
	global_load_dwordx4 v[16:19], v153, s[42:43]
	global_load_dwordx4 v[20:23], v153, s[42:43] offset:16
	v_cmp_ne_u32_e32 vcc, 0, v159
	v_add_u32_e32 v156, v154, v155
	v_add_u32_e32 v156, 0xfffff000, v156
	v_add_u32_e32 v157, 0x2800, v156
	v_lshlrev_b32_e32 v158, 12, v151
	v_add_u32_e32 v158, v158, v155
	v_mov_b32_e32 v24, 0
	v_mov_b32_e32 v25, 0
	v_mov_b32_e32 v26, 0
	v_mov_b32_e32 v27, 0
	v_mov_b32_e32 v60, 0
	v_mov_b32_e32 v61, 0
	v_mov_b32_e32 v62, 0
	v_mov_b32_e32 v63, 0
	s_and_saveexec_b64 s[20:21], vcc
	global_load_dwordx4 v[24:27], v156, s[66:67]
	s_or_b64 exec, exec, s[20:21]
	v_add_u32_e32 v156, 0x3000, v156
	global_load_dwordx4 v[28:31], v156, s[66:67]
	v_add_u32_e32 v156, 0x3000, v156
	global_load_dwordx4 v[32:35], v156, s[66:67]
	v_add_u32_e32 v159, 8, v151
	v_and_b32_e32 v159, 0xff8, v159
	global_load_dwordx4 v[64:67], v157, s[66:67]
	v_add_u32_e32 v157, 0x3000, v157
	v_add_u32_e32 v156, 0x3000, v156
	global_load_dwordx4 v[36:39], v156, s[66:67]
	global_load_dwordx4 v[68:71], v157, s[66:67]
	v_add_u32_e32 v157, 0x3000, v157
	v_add_u32_e32 v156, 0x3000, v156
	global_load_dwordx4 v[40:43], v156, s[66:67]
	global_load_dwordx4 v[72:75], v157, s[66:67]
	v_add_u32_e32 v157, 0x3000, v157
	v_add_u32_e32 v156, 0x3000, v156
	global_load_dwordx4 v[44:47], v156, s[66:67]
	global_load_dwordx4 v[76:79], v157, s[66:67]
	v_add_u32_e32 v157, 0x3000, v157
	v_add_u32_e32 v156, 0x3000, v156
	global_load_dwordx4 v[48:51], v156, s[66:67]
	global_load_dwordx4 v[80:83], v157, s[66:67]
	v_add_u32_e32 v157, 0x3000, v157
	v_add_u32_e32 v156, 0x3000, v156
	global_load_dwordx4 v[52:55], v156, s[66:67]
	global_load_dwordx4 v[84:87], v157, s[66:67]
	v_add_u32_e32 v157, 0x3000, v157
	v_add_u32_e32 v156, 0x3000, v156
	global_load_dwordx4 v[56:59], v156, s[66:67]
	global_load_dwordx4 v[88:91], v157, s[66:67]
	v_add_u32_e32 v157, 0x3000, v157
	v_add_u32_e32 v156, 0x3000, v156
	v_cmp_ne_u32_e32 vcc, 0, v159
	s_nop 3
	s_and_saveexec_b64 s[20:21], vcc
	global_load_dwordx4 v[60:63], v156, s[66:67]
	s_or_b64 exec, exec, s[20:21]
	global_load_dwordx4 v[92:95], v157, s[66:67]
	s_waitcnt vmcnt(14)
	v_lshlrev_b32_e32 v96, 16, v24
	v_and_b32_e32 v97, 0xffff0000, v24
	v_lshlrev_b32_e32 v98, 16, v25
	v_and_b32_e32 v99, 0xffff0000, v25
	v_lshlrev_b32_e32 v100, 16, v26
	v_and_b32_e32 v101, 0xffff0000, v26
	v_lshlrev_b32_e32 v102, 16, v27
	v_and_b32_e32 v103, 0xffff0000, v27
	v_lshlrev_b32_e32 v104, 16, v28
	v_and_b32_e32 v105, 0xffff0000, v28
	v_lshlrev_b32_e32 v106, 16, v29
	v_and_b32_e32 v107, 0xffff0000, v29
	v_lshlrev_b32_e32 v108, 16, v30
	v_and_b32_e32 v109, 0xffff0000, v30
	v_lshlrev_b32_e32 v110, 16, v31
	v_and_b32_e32 v111, 0xffff0000, v31
	v_lshlrev_b32_e32 v112, 16, v32
	v_and_b32_e32 v113, 0xffff0000, v32
	v_lshlrev_b32_e32 v114, 16, v33
	v_and_b32_e32 v115, 0xffff0000, v33
	v_lshlrev_b32_e32 v116, 16, v34
	v_and_b32_e32 v117, 0xffff0000, v34
	v_lshlrev_b32_e32 v118, 16, v35
	v_and_b32_e32 v119, 0xffff0000, v35
	v_lshlrev_b32_e32 v120, 16, v64
	v_and_b32_e32 v121, 0xffff0000, v64
	v_lshlrev_b32_e32 v122, 16, v65
	v_and_b32_e32 v123, 0xffff0000, v65
	v_lshlrev_b32_e32 v124, 16, v66
	v_and_b32_e32 v125, 0xffff0000, v66
	v_lshlrev_b32_e32 v126, 16, v67
	v_and_b32_e32 v127, 0xffff0000, v67
	v_pk_mul_f32 v[128:129], v[8:9], v[104:105]
	v_pk_mul_f32 v[130:131], v[10:11], v[106:107]
	v_pk_mul_f32 v[132:133], v[12:13], v[108:109]
	v_pk_mul_f32 v[134:135], v[14:15], v[110:111]
	v_pk_fma_f32 v[128:129], v[0:1], v[96:97], v[128:129]
	v_pk_fma_f32 v[130:131], v[2:3], v[98:99], v[130:131]
	v_pk_fma_f32 v[132:133], v[4:5], v[100:101], v[132:133]
	v_pk_fma_f32 v[134:135], v[6:7], v[102:103], v[134:135]
	v_pk_fma_f32 v[128:129], v[16:17], v[112:113], v[128:129]
	v_pk_fma_f32 v[130:131], v[18:19], v[114:115], v[130:131]
	v_pk_fma_f32 v[132:133], v[20:21], v[116:117], v[132:133]
	v_pk_fma_f32 v[134:135], v[22:23], v[118:119], v[134:135]
	v_pk_mul_f32 v[128:129], v[128:129], v[120:121]
	v_pk_mul_f32 v[130:131], v[130:131], v[122:123]
	v_pk_mul_f32 v[132:133], v[132:133], v[124:125]
	v_pk_mul_f32 v[134:135], v[134:135], v[126:127]
	v_cvt_pk_bf16_f32 v136, v128, v129
	v_cvt_pk_bf16_f32 v137, v130, v131
	v_cvt_pk_bf16_f32 v138, v132, v133
	v_cvt_pk_bf16_f32 v139, v134, v135
	global_store_dwordx4 v158, v[136:139], s[68:69] offset:2048 sc1
	v_add_u32_e32 v158, 0x1000, v158
	s_waitcnt vmcnt(13)
; __device__ __forceinline__ unsigned cvtpk(float lo, float hi) { f32x2_t v = {lo, hi}; bf16x2_t b = __builtin_convertvector(v, bf16x2_t); return __builtin_bit_cast(unsigned, b); }
; #define LDZ(row, z) do { const bf16x8 c_ = *reinterpret_cast<const bf16x8*>(proj + (long)(row) * LDP + 4096 + c8);     \
;     _Pragma("unroll") for (int e = 0; e < 8; ++e) z[e] = __uint_as_float(((unsigned)(unsigned short)c_[e]) << 16); } while (0)
; __device__ __forceinline__ void conv_tile(const bf16* __restrict__ proj, bf16* __restrict__ cat, const float* __restrict__ cw, long row0, int ch0, int lane) {
;     ...
;   for (int i = 0; i < 8; ++i) { const long row = r0 + i;
;     if (((row + 1) & (SEQ - 1)) == 0) {
; #pragma unroll
;       for (int e = 0; e < 8; ++e) zn[e] = 0.f;
;     } else LDZ(row + 1, zn);
;     const bf16x8 gb = *reinterpret_cast<const bf16x8*>(proj + row * LDP + 3072 + c8);
;     float y[8];
; #pragma unroll
;     for (int e = 0; e < 8; ++e) y[e] = __uint_as_float(((unsigned)(unsigned short)gb[e]) << 16) * (zp[e] * w0[e] + zc[e] * w1[e] + zn[e] * w2[e]);
;     u32x4 w; w.x = cvtpk(y[0], y[1]); w.y = cvtpk(y[2], y[3]); w.z = cvtpk(y[4], y[5]); w.w = cvtpk(y[6], y[7]);
;     *(u32x4*)(cat + row * LDC + 1024 + c8) = w;
; #pragma unroll
;     for (int e = 0; e < 8; ++e) { zp[e] = zc[e]; zc[e] = zn[e]; }
	v_lshlrev_b32_e32 v96, 16, v36
	v_and_b32_e32 v97, 0xffff0000, v36
	v_lshlrev_b32_e32 v98, 16, v37
	v_and_b32_e32 v99, 0xffff0000, v37
	v_lshlrev_b32_e32 v100, 16, v38
	v_and_b32_e32 v101, 0xffff0000, v38
	v_lshlrev_b32_e32 v102, 16, v39
	v_and_b32_e32 v103, 0xffff0000, v39
	v_lshlrev_b32_e32 v120, 16, v68
	v_and_b32_e32 v121, 0xffff0000, v68
	v_lshlrev_b32_e32 v122, 16, v69
	v_and_b32_e32 v123, 0xffff0000, v69
	v_lshlrev_b32_e32 v124, 16, v70
	v_and_b32_e32 v125, 0xffff0000, v70
	v_lshlrev_b32_e32 v126, 16, v71
	v_and_b32_e32 v127, 0xffff0000, v71
	v_pk_mul_f32 v[128:129], v[8:9], v[112:113]
	v_pk_mul_f32 v[130:131], v[10:11], v[114:115]
	v_pk_mul_f32 v[132:133], v[12:13], v[116:117]
	v_pk_mul_f32 v[134:135], v[14:15], v[118:119]
	v_pk_fma_f32 v[128:129], v[0:1], v[104:105], v[128:129]
	v_pk_fma_f32 v[130:131], v[2:3], v[106:107], v[130:131]
	v_pk_fma_f32 v[132:133], v[4:5], v[108:109], v[132:133]
	v_pk_fma_f32 v[134:135], v[6:7], v[110:111], v[134:135]
	v_pk_fma_f32 v[128:129], v[16:17], v[96:97], v[128:129]
	v_pk_fma_f32 v[130:131], v[18:19], v[98:99], v[130:131]
	v_pk_fma_f32 v[132:133], v[20:21], v[100:101], v[132:133]
	v_pk_fma_f32 v[134:135], v[22:23], v[102:103], v[134:135]
	v_pk_mul_f32 v[128:129], v[128:129], v[120:121]
	v_pk_mul_f32 v[130:131], v[130:131], v[122:123]
	v_pk_mul_f32 v[132:133], v[132:133], v[124:125]
	v_pk_mul_f32 v[134:135], v[134:135], v[126:127]
	v_cvt_pk_bf16_f32 v140, v128, v129
	v_cvt_pk_bf16_f32 v141, v130, v131
	v_cvt_pk_bf16_f32 v142, v132, v133
	v_cvt_pk_bf16_f32 v143, v134, v135
	global_store_dwordx4 v158, v[140:143], s[68:69] offset:2048 sc1
	v_add_u32_e32 v158, 0x1000, v158
	s_waitcnt vmcnt(12)
	v_lshlrev_b32_e32 v104, 16, v40
	v_and_b32_e32 v105, 0xffff0000, v40
	v_lshlrev_b32_e32 v106, 16, v41
	v_and_b32_e32 v107, 0xffff0000, v41
	v_lshlrev_b32_e32 v108, 16, v42
	v_and_b32_e32 v109, 0xffff0000, v42
	v_lshlrev_b32_e32 v110, 16, v43
	v_and_b32_e32 v111, 0xffff0000, v43
	v_lshlrev_b32_e32 v120, 16, v72
	v_and_b32_e32 v121, 0xffff0000, v72
	v_lshlrev_b32_e32 v122, 16, v73
	v_and_b32_e32 v123, 0xffff0000, v73
	v_lshlrev_b32_e32 v124, 16, v74
	v_and_b32_e32 v125, 0xffff0000, v74
	v_lshlrev_b32_e32 v126, 16, v75
	v_and_b32_e32 v127, 0xffff0000, v75
	v_pk_mul_f32 v[128:129], v[8:9], v[96:97]
	v_pk_mul_f32 v[130:131], v[10:11], v[98:99]
	v_pk_mul_f32 v[132:133], v[12:13], v[100:101]
	v_pk_mul_f32 v[134:135], v[14:15], v[102:103]
	v_pk_fma_f32 v[128:129], v[0:1], v[112:113], v[128:129]
	v_pk_fma_f32 v[130:131], v[2:3], v[114:115], v[130:131]
	v_pk_fma_f32 v[132:133], v[4:5], v[116:117], v[132:133]
	v_pk_fma_f32 v[134:135], v[6:7], v[118:119], v[134:135]
	v_pk_fma_f32 v[128:129], v[16:17], v[104:105], v[128:129]
	v_pk_fma_f32 v[130:131], v[18:19], v[106:107], v[130:131]
	v_pk_fma_f32 v[132:133], v[20:21], v[108:109], v[132:133]
	v_pk_fma_f32 v[134:135], v[22:23], v[110:111], v[134:135]
	v_pk_mul_f32 v[128:129], v[128:129], v[120:121]
	v_pk_mul_f32 v[130:131], v[130:131], v[122:123]
	v_pk_mul_f32 v[132:133], v[132:133], v[124:125]
	v_pk_mul_f32 v[134:135], v[134:135], v[126:127]
	v_cvt_pk_bf16_f32 v136, v128, v129
	v_cvt_pk_bf16_f32 v137, v130, v131
	v_cvt_pk_bf16_f32 v138, v132, v133
	v_cvt_pk_bf16_f32 v139, v134, v135
	global_store_dwordx4 v158, v[136:139], s[68:69] offset:2048 sc1
	v_add_u32_e32 v158, 0x1000, v158
	s_waitcnt vmcnt(11)
	v_lshlrev_b32_e32 v112, 16, v44
	v_and_b32_e32 v113, 0xffff0000, v44
	v_lshlrev_b32_e32 v114, 16, v45
	v_and_b32_e32 v115, 0xffff0000, v45
	v_lshlrev_b32_e32 v116, 16, v46
	v_and_b32_e32 v117, 0xffff0000, v46
	v_lshlrev_b32_e32 v118, 16, v47
	v_and_b32_e32 v119, 0xffff0000, v47
	v_lshlrev_b32_e32 v120, 16, v76
	v_and_b32_e32 v121, 0xffff0000, v76
	v_lshlrev_b32_e32 v122, 16, v77
	v_and_b32_e32 v123, 0xffff0000, v77
	v_lshlrev_b32_e32 v124, 16, v78
	v_and_b32_e32 v125, 0xffff0000, v78
	v_lshlrev_b32_e32 v126, 16, v79
	v_and_b32_e32 v127, 0xffff0000, v79
	v_pk_mul_f32 v[128:129], v[8:9], v[104:105]
	v_pk_mul_f32 v[130:131], v[10:11], v[106:107]
	v_pk_mul_f32 v[132:133], v[12:13], v[108:109]
	v_pk_mul_f32 v[134:135], v[14:15], v[110:111]
	v_pk_fma_f32 v[128:129], v[0:1], v[96:97], v[128:129]
	v_pk_fma_f32 v[130:131], v[2:3], v[98:99], v[130:131]
	v_pk_fma_f32 v[132:133], v[4:5], v[100:101], v[132:133]
	v_pk_fma_f32 v[134:135], v[6:7], v[102:103], v[134:135]
	v_pk_fma_f32 v[128:129], v[16:17], v[112:113], v[128:129]
	v_pk_fma_f32 v[130:131], v[18:19], v[114:115], v[130:131]
	v_pk_fma_f32 v[132:133], v[20:21], v[116:117], v[132:133]
	v_pk_fma_f32 v[134:135], v[22:23], v[118:119], v[134:135]
	v_pk_mul_f32 v[128:129], v[128:129], v[120:121]
	v_pk_mul_f32 v[130:131], v[130:131], v[122:123]
	v_pk_mul_f32 v[132:133], v[132:133], v[124:125]
	v_pk_mul_f32 v[134:135], v[134:135], v[126:127]
	v_cvt_pk_bf16_f32 v140, v128, v129
	v_cvt_pk_bf16_f32 v141, v130, v131
	v_cvt_pk_bf16_f32 v142, v132, v133
	v_cvt_pk_bf16_f32 v143, v134, v135
	global_store_dwordx4 v158, v[140:143], s[68:69] offset:2048 sc1
	v_add_u32_e32 v158, 0x1000, v158
	s_waitcnt vmcnt(10)
; __device__ __forceinline__ unsigned cvtpk(float lo, float hi) { f32x2_t v = {lo, hi}; bf16x2_t b = __builtin_convertvector(v, bf16x2_t); return __builtin_bit_cast(unsigned, b); }
; #define LDZ(row, z) do { const bf16x8 c_ = *reinterpret_cast<const bf16x8*>(proj + (long)(row) * LDP + 4096 + c8);     \
;     _Pragma("unroll") for (int e = 0; e < 8; ++e) z[e] = __uint_as_float(((unsigned)(unsigned short)c_[e]) << 16); } while (0)
; __device__ __forceinline__ void conv_tile(const bf16* __restrict__ proj, bf16* __restrict__ cat, const float* __restrict__ cw, long row0, int ch0, int lane) {
;     ...
;   for (int i = 0; i < 8; ++i) { const long row = r0 + i;
;     if (((row + 1) & (SEQ - 1)) == 0) {
; #pragma unroll
;       for (int e = 0; e < 8; ++e) zn[e] = 0.f;
;     } else LDZ(row + 1, zn);
;     const bf16x8 gb = *reinterpret_cast<const bf16x8*>(proj + row * LDP + 3072 + c8);
;     float y[8];
; #pragma unroll
;     for (int e = 0; e < 8; ++e) y[e] = __uint_as_float(((unsigned)(unsigned short)gb[e]) << 16) * (zp[e] * w0[e] + zc[e] * w1[e] + zn[e] * w2[e]);
;     u32x4 w; w.x = cvtpk(y[0], y[1]); w.y = cvtpk(y[2], y[3]); w.z = cvtpk(y[4], y[5]); w.w = cvtpk(y[6], y[7]);
;     *(u32x4*)(cat + row * LDC + 1024 + c8) = w;
; #pragma unroll
;     for (int e = 0; e < 8; ++e) { zp[e] = zc[e]; zc[e] = zn[e]; }
	v_lshlrev_b32_e32 v96, 16, v48
	v_and_b32_e32 v97, 0xffff0000, v48
	v_lshlrev_b32_e32 v98, 16, v49
	v_and_b32_e32 v99, 0xffff0000, v49
	v_lshlrev_b32_e32 v100, 16, v50
	v_and_b32_e32 v101, 0xffff0000, v50
	v_lshlrev_b32_e32 v102, 16, v51
	v_and_b32_e32 v103, 0xffff0000, v51
	v_lshlrev_b32_e32 v120, 16, v80
	v_and_b32_e32 v121, 0xffff0000, v80
	v_lshlrev_b32_e32 v122, 16, v81
	v_and_b32_e32 v123, 0xffff0000, v81
	v_lshlrev_b32_e32 v124, 16, v82
	v_and_b32_e32 v125, 0xffff0000, v82
	v_lshlrev_b32_e32 v126, 16, v83
	v_and_b32_e32 v127, 0xffff0000, v83
	v_pk_mul_f32 v[128:129], v[8:9], v[112:113]
	v_pk_mul_f32 v[130:131], v[10:11], v[114:115]
	v_pk_mul_f32 v[132:133], v[12:13], v[116:117]
	v_pk_mul_f32 v[134:135], v[14:15], v[118:119]
	v_pk_fma_f32 v[128:129], v[0:1], v[104:105], v[128:129]
	v_pk_fma_f32 v[130:131], v[2:3], v[106:107], v[130:131]
	v_pk_fma_f32 v[132:133], v[4:5], v[108:109], v[132:133]
	v_pk_fma_f32 v[134:135], v[6:7], v[110:111], v[134:135]
	v_pk_fma_f32 v[128:129], v[16:17], v[96:97], v[128:129]
	v_pk_fma_f32 v[130:131], v[18:19], v[98:99], v[130:131]
	v_pk_fma_f32 v[132:133], v[20:21], v[100:101], v[132:133]
	v_pk_fma_f32 v[134:135], v[22:23], v[102:103], v[134:135]
	v_pk_mul_f32 v[128:129], v[128:129], v[120:121]
	v_pk_mul_f32 v[130:131], v[130:131], v[122:123]
	v_pk_mul_f32 v[132:133], v[132:133], v[124:125]
	v_pk_mul_f32 v[134:135], v[134:135], v[126:127]
	v_cvt_pk_bf16_f32 v136, v128, v129
	v_cvt_pk_bf16_f32 v137, v130, v131
	v_cvt_pk_bf16_f32 v138, v132, v133
	v_cvt_pk_bf16_f32 v139, v134, v135
	global_store_dwordx4 v158, v[136:139], s[68:69] offset:2048 sc1
	v_add_u32_e32 v158, 0x1000, v158
	s_waitcnt vmcnt(9)
	v_lshlrev_b32_e32 v104, 16, v52
	v_and_b32_e32 v105, 0xffff0000, v52
	v_lshlrev_b32_e32 v106, 16, v53
	v_and_b32_e32 v107, 0xffff0000, v53
	v_lshlrev_b32_e32 v108, 16, v54
	v_and_b32_e32 v109, 0xffff0000, v54
	v_lshlrev_b32_e32 v110, 16, v55
	v_and_b32_e32 v111, 0xffff0000, v55
	v_lshlrev_b32_e32 v120, 16, v84
	v_and_b32_e32 v121, 0xffff0000, v84
	v_lshlrev_b32_e32 v122, 16, v85
	v_and_b32_e32 v123, 0xffff0000, v85
	v_lshlrev_b32_e32 v124, 16, v86
	v_and_b32_e32 v125, 0xffff0000, v86
	v_lshlrev_b32_e32 v126, 16, v87
	v_and_b32_e32 v127, 0xffff0000, v87
	v_pk_mul_f32 v[128:129], v[8:9], v[96:97]
	v_pk_mul_f32 v[130:131], v[10:11], v[98:99]
	v_pk_mul_f32 v[132:133], v[12:13], v[100:101]
	v_pk_mul_f32 v[134:135], v[14:15], v[102:103]
	v_pk_fma_f32 v[128:129], v[0:1], v[112:113], v[128:129]
	v_pk_fma_f32 v[130:131], v[2:3], v[114:115], v[130:131]
	v_pk_fma_f32 v[132:133], v[4:5], v[116:117], v[132:133]
	v_pk_fma_f32 v[134:135], v[6:7], v[118:119], v[134:135]
	v_pk_fma_f32 v[128:129], v[16:17], v[104:105], v[128:129]
	v_pk_fma_f32 v[130:131], v[18:19], v[106:107], v[130:131]
	v_pk_fma_f32 v[132:133], v[20:21], v[108:109], v[132:133]
	v_pk_fma_f32 v[134:135], v[22:23], v[110:111], v[134:135]
	v_pk_mul_f32 v[128:129], v[128:129], v[120:121]
	v_pk_mul_f32 v[130:131], v[130:131], v[122:123]
	v_pk_mul_f32 v[132:133], v[132:133], v[124:125]
	v_pk_mul_f32 v[134:135], v[134:135], v[126:127]
	v_cvt_pk_bf16_f32 v140, v128, v129
	v_cvt_pk_bf16_f32 v141, v130, v131
	v_cvt_pk_bf16_f32 v142, v132, v133
	v_cvt_pk_bf16_f32 v143, v134, v135
	global_store_dwordx4 v158, v[140:143], s[68:69] offset:2048 sc1
	v_add_u32_e32 v158, 0x1000, v158
	s_waitcnt vmcnt(8)
	v_lshlrev_b32_e32 v112, 16, v56
	v_and_b32_e32 v113, 0xffff0000, v56
	v_lshlrev_b32_e32 v114, 16, v57
	v_and_b32_e32 v115, 0xffff0000, v57
	v_lshlrev_b32_e32 v116, 16, v58
	v_and_b32_e32 v117, 0xffff0000, v58
	v_lshlrev_b32_e32 v118, 16, v59
	v_and_b32_e32 v119, 0xffff0000, v59
	v_lshlrev_b32_e32 v120, 16, v88
	v_and_b32_e32 v121, 0xffff0000, v88
	v_lshlrev_b32_e32 v122, 16, v89
	v_and_b32_e32 v123, 0xffff0000, v89
	v_lshlrev_b32_e32 v124, 16, v90
	v_and_b32_e32 v125, 0xffff0000, v90
	v_lshlrev_b32_e32 v126, 16, v91
	v_and_b32_e32 v127, 0xffff0000, v91
	v_pk_mul_f32 v[128:129], v[8:9], v[104:105]
	v_pk_mul_f32 v[130:131], v[10:11], v[106:107]
	v_pk_mul_f32 v[132:133], v[12:13], v[108:109]
	v_pk_mul_f32 v[134:135], v[14:15], v[110:111]
	v_pk_fma_f32 v[128:129], v[0:1], v[96:97], v[128:129]
	v_pk_fma_f32 v[130:131], v[2:3], v[98:99], v[130:131]
	v_pk_fma_f32 v[132:133], v[4:5], v[100:101], v[132:133]
	v_pk_fma_f32 v[134:135], v[6:7], v[102:103], v[134:135]
	v_pk_fma_f32 v[128:129], v[16:17], v[112:113], v[128:129]
	v_pk_fma_f32 v[130:131], v[18:19], v[114:115], v[130:131]
	v_pk_fma_f32 v[132:133], v[20:21], v[116:117], v[132:133]
	v_pk_fma_f32 v[134:135], v[22:23], v[118:119], v[134:135]
	v_pk_mul_f32 v[128:129], v[128:129], v[120:121]
	v_pk_mul_f32 v[130:131], v[130:131], v[122:123]
	v_pk_mul_f32 v[132:133], v[132:133], v[124:125]
	v_pk_mul_f32 v[134:135], v[134:135], v[126:127]
	v_cvt_pk_bf16_f32 v136, v128, v129
	v_cvt_pk_bf16_f32 v137, v130, v131
	v_cvt_pk_bf16_f32 v138, v132, v133
	v_cvt_pk_bf16_f32 v139, v134, v135
	global_store_dwordx4 v158, v[136:139], s[68:69] offset:2048 sc1
	v_add_u32_e32 v158, 0x1000, v158
	s_waitcnt vmcnt(7)
	v_lshlrev_b32_e32 v96, 16, v60
	v_and_b32_e32 v97, 0xffff0000, v60
	v_lshlrev_b32_e32 v98, 16, v61
	v_and_b32_e32 v99, 0xffff0000, v61
	v_lshlrev_b32_e32 v100, 16, v62
	v_and_b32_e32 v101, 0xffff0000, v62
	v_lshlrev_b32_e32 v102, 16, v63
	v_and_b32_e32 v103, 0xffff0000, v63
	v_lshlrev_b32_e32 v120, 16, v92
	v_and_b32_e32 v121, 0xffff0000, v92
	v_lshlrev_b32_e32 v122, 16, v93
	v_and_b32_e32 v123, 0xffff0000, v93
	v_lshlrev_b32_e32 v124, 16, v94
	v_and_b32_e32 v125, 0xffff0000, v94
	v_lshlrev_b32_e32 v126, 16, v95
	v_and_b32_e32 v127, 0xffff0000, v95
	v_pk_mul_f32 v[128:129], v[8:9], v[112:113]
	v_pk_mul_f32 v[130:131], v[10:11], v[114:115]
	v_pk_mul_f32 v[132:133], v[12:13], v[116:117]
	v_pk_mul_f32 v[134:135], v[14:15], v[118:119]
	v_pk_fma_f32 v[128:129], v[0:1], v[104:105], v[128:129]
	v_pk_fma_f32 v[130:131], v[2:3], v[106:107], v[130:131]
	v_pk_fma_f32 v[132:133], v[4:5], v[108:109], v[132:133]
	v_pk_fma_f32 v[134:135], v[6:7], v[110:111], v[134:135]
	v_pk_fma_f32 v[128:129], v[16:17], v[96:97], v[128:129]
	v_pk_fma_f32 v[130:131], v[18:19], v[98:99], v[130:131]
	v_pk_fma_f32 v[132:133], v[20:21], v[100:101], v[132:133]
	v_pk_fma_f32 v[134:135], v[22:23], v[102:103], v[134:135]
	v_pk_mul_f32 v[128:129], v[128:129], v[120:121]
	v_pk_mul_f32 v[130:131], v[130:131], v[122:123]
	v_pk_mul_f32 v[132:133], v[132:133], v[124:125]
	v_pk_mul_f32 v[134:135], v[134:135], v[126:127]
	v_cvt_pk_bf16_f32 v140, v128, v129
	v_cvt_pk_bf16_f32 v141, v130, v131
	v_cvt_pk_bf16_f32 v142, v132, v133
	v_cvt_pk_bf16_f32 v143, v134, v135
	global_store_dwordx4 v158, v[140:143], s[68:69] offset:2048 sc1
	s_mov_b64 s[20:21], 0
; __device__ __forceinline__ int crow(int r, int hi) { return (r & 3) + 8 * (r >> 2) + 4 * hi; }
; __device__ __forceinline__ void attn_unit(const bf16* __restrict__ proj, bf16* __restrict__ cat, int b, int h, int qb, float lam, float oscale, const float* __restrict__ subln, const float* __restrict__ cw, char* lds) {
;     ...
;   if (mp == 0) {
;     float g[4];
; #pragma unroll
;     for (int d0 = 0; d0 < 4; ++d0) g[d0] = subln[d0 * 32 + r32] * oscale;
;     bf16* stg = (bf16*)(lds + OFF_STG) + rg * (32 * 128);
; #pragma unroll
;     for (int r = 0; r < 16; ++r) { float s = 0.f;
; #pragma unroll
;       for (int d0 = 0; d0 < 4; ++d0) { const float v = o[d0][r] * rli[r] - X[(d0 * 16 + r) * 64 + lane]; o[d0][r] = v; s += v * v; }
;       s += __shfl_xor(s, 1); s += __shfl_xor(s, 2); s += __shfl_xor(s, 4); s += __shfl_xor(s, 8); s += __shfl_xor(s, 16);
;       const float rs = __builtin_amdgcn_rsqf(s * (1.f / 128.f) + 1e-6f); const int orow = crow(r, hi);
; #pragma unroll
;       for (int d0 = 0; d0 < 4; ++d0) stg[orow * 128 + d0 * 32 + r32] = __float2bfloat16(o[d0][r] * rs * g[d0]); }
.LBB0_248:
	s_and_b64 vcc, exec, s[20:21]
	s_cbranch_vccz .LBB0_207
	v_lshlrev_b32_e32 v67, 2, v174
	global_load_dword v64, v67, s[40:41]
	global_load_dword v65, v67, s[40:41] offset:128
	global_load_dword v66, v67, s[40:41] offset:256
	ds_read2st64_b32 v[70:71], v136 offset1:1
	ds_read2st64_b32 v[72:73], v136 offset0:16 offset1:17
	ds_read2st64_b32 v[74:75], v136 offset0:32 offset1:33
	ds_read2st64_b32 v[76:77], v136 offset0:48 offset1:49
	global_load_dword v67, v67, s[40:41] offset:384
	s_lshl_b32 s20, s29, 13
	s_add_i32 s20, s20, 0
	s_add_i32 s20, s20, 0x10000
	v_lshlrev_b32_e32 v68, 10, v179
	v_lshlrev_b32_e32 v69, 1, v174
	s_waitcnt lgkmcnt(0)
	v_fma_f32 v48, v48, v150, -v72
	v_add3_u32 v68, s20, v68, v69
	v_fma_f32 v0, v0, v150, -v70
	v_mul_f32_e32 v69, v48, v48
	v_fmac_f32_e32 v69, v0, v0
	s_waitcnt lgkmcnt(0)
	v_fma_f32 v32, v32, v150, -v74
	v_fmac_f32_e32 v69, v32, v32
	s_waitcnt lgkmcnt(0)
	v_fma_f32 v16, v16, v150, -v76
	v_fmac_f32_e32 v69, v16, v16
	v_fma_f32 v17, v17, v149, -v77
	s_lshl_b64 s[24:25], s[44:45], 12
	s_add_u32 s21, s68, s24
	s_addc_u32 s25, s69, s25
	s_waitcnt lgkmcnt(0)
	s_nop 1
	v_add_f32_dpp v69, v69, v69 quad_perm:[1,0,3,2] row_mask:0xf bank_mask:0xf
	s_lshl_b32 s24, s28, 1
	s_add_u32 s24, s21, s24
	s_addc_u32 s25, s25, 0
	s_waitcnt lgkmcnt(0)
	s_nop 1
	v_add_f32_dpp v69, v69, v69 quad_perm:[2,3,0,1] row_mask:0xf bank_mask:0xf
	s_waitcnt lgkmcnt(0)
	s_nop 1
	v_add_f32_dpp v69, v69, v69 row_half_mirror row_mask:0xf bank_mask:0xf
	s_waitcnt lgkmcnt(0)
	s_nop 1
	v_add_f32_dpp v69, v69, v69 row_mirror row_mask:0xf bank_mask:0xf
	ds_bpermute_b32 v70, v208, v69
	s_waitcnt lgkmcnt(0)
	v_add_f32_e32 v69, v69, v70
	v_fmamk_f32 v69, v69, 0x3c000000, v194
	v_rsq_f32_e32 v69, v69
	s_waitcnt vmcnt(3)
	v_mul_f32_e32 v64, v175, v64
	v_mul_f32_e32 v0, v0, v69
	v_mul_f32_e32 v0, v64, v0
	v_cvt_pk_bf16_f32 v0, v0, s0
	s_waitcnt vmcnt(2)
	v_mul_f32_e32 v65, v175, v65
	ds_write_b16 v68, v0
	v_mul_f32_e32 v0, v48, v69
	v_mul_f32_e32 v0, v65, v0
	v_cvt_pk_bf16_f32 v0, v0, s0
	s_waitcnt vmcnt(1)
	v_mul_f32_e32 v66, v175, v66
	ds_write_b16 v68, v0 offset:64
	v_mul_f32_e32 v0, v32, v69
	v_mul_f32_e32 v0, v66, v0
	v_cvt_pk_bf16_f32 v0, v0, s0
	s_waitcnt vmcnt(0)
	v_mul_f32_e32 v67, v175, v67
	ds_write_b16 v68, v0 offset:128
	v_mul_f32_e32 v0, v16, v69
	v_mul_f32_e32 v0, v67, v0
	v_cvt_pk_bf16_f32 v0, v0, s0
	ds_write_b16 v68, v0 offset:192
	v_fma_f32 v0, v1, v149, -v71
	v_fma_f32 v1, v49, v149, -v73
	v_mul_f32_e32 v16, v1, v1
	v_fmac_f32_e32 v16, v0, v0
	v_fma_f32 v32, v33, v149, -v75
	v_fmac_f32_e32 v16, v32, v32
	v_fmac_f32_e32 v16, v17, v17
	ds_read2st64_b32 v[48:49], v136 offset0:50 offset1:51
	s_waitcnt lgkmcnt(0)
	s_nop 1
	v_add_f32_dpp v16, v16, v16 quad_perm:[1,0,3,2] row_mask:0xf bank_mask:0xf
	s_waitcnt lgkmcnt(0)
	v_fma_f32 v18, v18, v148, -v48
	s_waitcnt lgkmcnt(0)
	s_nop 1
	v_add_f32_dpp v16, v16, v16 quad_perm:[2,3,0,1] row_mask:0xf bank_mask:0xf
	s_waitcnt lgkmcnt(0)
	s_nop 1
	v_add_f32_dpp v16, v16, v16 row_half_mirror row_mask:0xf bank_mask:0xf
	s_waitcnt lgkmcnt(0)
	s_nop 1
	v_add_f32_dpp v16, v16, v16 row_mirror row_mask:0xf bank_mask:0xf
	ds_bpermute_b32 v33, v208, v16
	s_waitcnt lgkmcnt(0)
	v_add_f32_e32 v16, v16, v33
	v_fmamk_f32 v16, v16, 0x3c000000, v194
	v_rsq_f32_e32 v16, v16
	s_nop 0
	v_mul_f32_e32 v0, v0, v16
	v_mul_f32_e32 v0, v64, v0
	v_cvt_pk_bf16_f32 v0, v0, s0
	ds_write_b16 v68, v0 offset:256
	v_mul_f32_e32 v0, v1, v16
	v_mul_f32_e32 v0, v65, v0
	v_cvt_pk_bf16_f32 v0, v0, s0
	ds_write_b16 v68, v0 offset:320
	v_mul_f32_e32 v0, v32, v16
	v_mul_f32_e32 v0, v66, v0
	v_cvt_pk_bf16_f32 v0, v0, s0
	ds_write_b16 v68, v0 offset:384
	v_mul_f32_e32 v0, v17, v16
	v_mul_f32_e32 v0, v67, v0
	v_cvt_pk_bf16_f32 v0, v0, s0
	ds_write_b16 v68, v0 offset:448
	ds_read2st64_b32 v[0:1], v136 offset0:2 offset1:3
	ds_read2st64_b32 v[16:17], v136 offset0:18 offset1:19
	ds_read2st64_b32 v[32:33], v136 offset0:34 offset1:35
	s_waitcnt lgkmcnt(0)
	v_fma_f32 v0, v2, v148, -v0
	s_waitcnt lgkmcnt(0)
	v_fma_f32 v2, v50, v148, -v16
	v_mul_f32_e32 v16, v2, v2
	v_fmac_f32_e32 v16, v0, v0
	s_waitcnt lgkmcnt(0)
	v_fma_f32 v32, v34, v148, -v32
	v_fmac_f32_e32 v16, v32, v32
	v_fmac_f32_e32 v16, v18, v18
	s_waitcnt lgkmcnt(0)
	s_nop 1
	v_add_f32_dpp v16, v16, v16 quad_perm:[1,0,3,2] row_mask:0xf bank_mask:0xf
	s_waitcnt lgkmcnt(0)
	s_nop 1
	v_add_f32_dpp v16, v16, v16 quad_perm:[2,3,0,1] row_mask:0xf bank_mask:0xf
	s_waitcnt lgkmcnt(0)
	s_nop 1
	v_add_f32_dpp v16, v16, v16 row_half_mirror row_mask:0xf bank_mask:0xf
	s_waitcnt lgkmcnt(0)
	s_nop 1
	v_add_f32_dpp v16, v16, v16 row_mirror row_mask:0xf bank_mask:0xf
	ds_bpermute_b32 v34, v208, v16
	s_waitcnt lgkmcnt(0)
	v_add_f32_e32 v16, v16, v34
	v_fmamk_f32 v16, v16, 0x3c000000, v194
	v_rsq_f32_e32 v16, v16
	s_nop 0
	v_mul_f32_e32 v0, v0, v16
	v_mul_f32_e32 v0, v64, v0
	v_cvt_pk_bf16_f32 v0, v0, s0
	ds_write_b16 v68, v0 offset:512
	v_mul_f32_e32 v0, v2, v16
	v_mul_f32_e32 v0, v65, v0
	v_cvt_pk_bf16_f32 v0, v0, s0
	ds_write_b16 v68, v0 offset:576
	v_mul_f32_e32 v0, v32, v16
	v_mul_f32_e32 v0, v66, v0
	v_cvt_pk_bf16_f32 v0, v0, s0
	ds_write_b16 v68, v0 offset:640
	v_mul_f32_e32 v0, v18, v16
	v_mul_f32_e32 v0, v67, v0
	v_cvt_pk_bf16_f32 v0, v0, s0
	ds_write_b16 v68, v0 offset:704
	v_fma_f32 v0, v3, v147, -v1
	v_fma_f32 v1, v51, v147, -v17
	v_mul_f32_e32 v2, v1, v1
	v_fmac_f32_e32 v2, v0, v0
	v_fma_f32 v3, v35, v147, -v33
	v_fmac_f32_e32 v2, v3, v3
	v_fma_f32 v16, v19, v147, -v49
	v_fmac_f32_e32 v2, v16, v16
	ds_read2st64_b32 v[18:19], v136 offset0:52 offset1:53
	s_waitcnt lgkmcnt(0)
	s_nop 1
	v_add_f32_dpp v2, v2, v2 quad_perm:[1,0,3,2] row_mask:0xf bank_mask:0xf
	s_waitcnt lgkmcnt(0)
; __device__ __forceinline__ int crow(int r, int hi) { return (r & 3) + 8 * (r >> 2) + 4 * hi; }
; __device__ __forceinline__ void attn_unit(const bf16* __restrict__ proj, bf16* __restrict__ cat, int b, int h, int qb, float lam, float oscale, const float* __restrict__ subln, const float* __restrict__ cw, char* lds) {
;     ...
;     for (int r = 0; r < 16; ++r) { float s = 0.f;
; #pragma unroll
;       for (int d0 = 0; d0 < 4; ++d0) { const float v = o[d0][r] * rli[r] - X[(d0 * 16 + r) * 64 + lane]; o[d0][r] = v; s += v * v; }
;       s += __shfl_xor(s, 1); s += __shfl_xor(s, 2); s += __shfl_xor(s, 4); s += __shfl_xor(s, 8); s += __shfl_xor(s, 16);
;       const float rs = __builtin_amdgcn_rsqf(s * (1.f / 128.f) + 1e-6f); const int orow = crow(r, hi);
; #pragma unroll
;       for (int d0 = 0; d0 < 4; ++d0) stg[orow * 128 + d0 * 32 + r32] = __float2bfloat16(o[d0][r] * rs * g[d0]); }
	v_fma_f32 v18, v20, v146, -v18
	s_waitcnt lgkmcnt(0)
	s_nop 1
	v_add_f32_dpp v2, v2, v2 quad_perm:[2,3,0,1] row_mask:0xf bank_mask:0xf
	s_waitcnt lgkmcnt(0)
	s_nop 1
	v_add_f32_dpp v2, v2, v2 row_half_mirror row_mask:0xf bank_mask:0xf
	s_waitcnt lgkmcnt(0)
	s_nop 1
	v_add_f32_dpp v2, v2, v2 row_mirror row_mask:0xf bank_mask:0xf
	ds_bpermute_b32 v17, v208, v2
	s_waitcnt lgkmcnt(0)
	v_add_f32_e32 v2, v2, v17
	v_fmamk_f32 v2, v2, 0x3c000000, v194
	v_rsq_f32_e32 v2, v2
	s_nop 0
	v_mul_f32_e32 v0, v0, v2
	v_mul_f32_e32 v0, v64, v0
	v_cvt_pk_bf16_f32 v0, v0, s0
	ds_write_b16 v68, v0 offset:768
	v_mul_f32_e32 v0, v1, v2
	v_mul_f32_e32 v0, v65, v0
	v_cvt_pk_bf16_f32 v0, v0, s0
	ds_write_b16 v68, v0 offset:832
	v_mul_f32_e32 v0, v3, v2
	v_mul_f32_e32 v0, v66, v0
	v_cvt_pk_bf16_f32 v0, v0, s0
	ds_write_b16 v68, v0 offset:896
	v_mul_f32_e32 v0, v16, v2
	v_mul_f32_e32 v0, v67, v0
	v_cvt_pk_bf16_f32 v0, v0, s0
	ds_write_b16 v68, v0 offset:960
	ds_read2st64_b32 v[0:1], v136 offset0:4 offset1:5
	ds_read2st64_b32 v[2:3], v136 offset0:20 offset1:21
	ds_read2st64_b32 v[16:17], v136 offset0:36 offset1:37
	s_waitcnt lgkmcnt(0)
	v_fma_f32 v0, v4, v146, -v0
	s_waitcnt lgkmcnt(0)
	v_fma_f32 v2, v52, v146, -v2
	v_mul_f32_e32 v4, v2, v2
	v_fmac_f32_e32 v4, v0, v0
	s_waitcnt lgkmcnt(0)
	v_fma_f32 v16, v36, v146, -v16
	v_fmac_f32_e32 v4, v16, v16
	v_fmac_f32_e32 v4, v18, v18
	s_waitcnt lgkmcnt(0)
	s_nop 1
	v_add_f32_dpp v4, v4, v4 quad_perm:[1,0,3,2] row_mask:0xf bank_mask:0xf
	s_waitcnt lgkmcnt(0)
	s_nop 1
	v_add_f32_dpp v4, v4, v4 quad_perm:[2,3,0,1] row_mask:0xf bank_mask:0xf
	s_waitcnt lgkmcnt(0)
	s_nop 1
	v_add_f32_dpp v4, v4, v4 row_half_mirror row_mask:0xf bank_mask:0xf
	s_waitcnt lgkmcnt(0)
	s_nop 1
	v_add_f32_dpp v4, v4, v4 row_mirror row_mask:0xf bank_mask:0xf
	ds_bpermute_b32 v20, v208, v4
	s_waitcnt lgkmcnt(0)
	v_add_f32_e32 v4, v4, v20
	v_fmamk_f32 v4, v4, 0x3c000000, v194
	v_rsq_f32_e32 v4, v4
	s_nop 0
	v_mul_f32_e32 v0, v0, v4
	v_mul_f32_e32 v0, v64, v0
	v_cvt_pk_bf16_f32 v0, v0, s0
	ds_write_b16 v68, v0 offset:2048
	v_mul_f32_e32 v0, v2, v4
	v_mul_f32_e32 v0, v65, v0
	v_cvt_pk_bf16_f32 v0, v0, s0
	ds_write_b16 v68, v0 offset:2112
	v_mul_f32_e32 v0, v16, v4
	v_mul_f32_e32 v0, v66, v0
	v_cvt_pk_bf16_f32 v0, v0, s0
	ds_write_b16 v68, v0 offset:2176
	v_mul_f32_e32 v0, v18, v4
	v_mul_f32_e32 v0, v67, v0
	v_cvt_pk_bf16_f32 v0, v0, s0
	ds_write_b16 v68, v0 offset:2240
	v_fma_f32 v0, v5, v145, -v1
	v_fma_f32 v1, v53, v145, -v3
	v_mul_f32_e32 v2, v1, v1
	v_fmac_f32_e32 v2, v0, v0
	v_fma_f32 v3, v37, v145, -v17
	v_fmac_f32_e32 v2, v3, v3
	v_fma_f32 v4, v21, v145, -v19
	v_fmac_f32_e32 v2, v4, v4
	ds_read2st64_b32 v[16:17], v136 offset0:54 offset1:55
	s_waitcnt lgkmcnt(0)
	s_nop 1
	v_add_f32_dpp v2, v2, v2 quad_perm:[1,0,3,2] row_mask:0xf bank_mask:0xf
	s_waitcnt lgkmcnt(0)
	v_fma_f32 v16, v22, v144, -v16
	s_waitcnt lgkmcnt(0)
	s_nop 1
	v_add_f32_dpp v2, v2, v2 quad_perm:[2,3,0,1] row_mask:0xf bank_mask:0xf
	s_waitcnt lgkmcnt(0)
	s_nop 1
	v_add_f32_dpp v2, v2, v2 row_half_mirror row_mask:0xf bank_mask:0xf
	s_waitcnt lgkmcnt(0)
	s_nop 1
	v_add_f32_dpp v2, v2, v2 row_mirror row_mask:0xf bank_mask:0xf
	ds_bpermute_b32 v5, v208, v2
	s_waitcnt lgkmcnt(0)
	v_add_f32_e32 v2, v2, v5
	v_fmamk_f32 v2, v2, 0x3c000000, v194
	v_rsq_f32_e32 v2, v2
	s_nop 0
	v_mul_f32_e32 v0, v0, v2
	v_mul_f32_e32 v0, v64, v0
	v_cvt_pk_bf16_f32 v0, v0, s0
	ds_write_b16 v68, v0 offset:2304
	v_mul_f32_e32 v0, v1, v2
	v_mul_f32_e32 v0, v65, v0
	v_cvt_pk_bf16_f32 v0, v0, s0
	ds_write_b16 v68, v0 offset:2368
	v_mul_f32_e32 v0, v3, v2
	v_mul_f32_e32 v0, v66, v0
	v_cvt_pk_bf16_f32 v0, v0, s0
	ds_write_b16 v68, v0 offset:2432
	v_mul_f32_e32 v0, v4, v2
	v_mul_f32_e32 v0, v67, v0
	v_cvt_pk_bf16_f32 v0, v0, s0
	ds_write_b16 v68, v0 offset:2496
	ds_read2st64_b32 v[0:1], v136 offset0:6 offset1:7
	ds_read2st64_b32 v[2:3], v136 offset0:22 offset1:23
	ds_read2st64_b32 v[4:5], v136 offset0:38 offset1:39
	s_waitcnt lgkmcnt(0)
	v_fma_f32 v0, v6, v144, -v0
	s_waitcnt lgkmcnt(0)
	v_fma_f32 v2, v54, v144, -v2
	v_mul_f32_e32 v6, v2, v2
	v_fmac_f32_e32 v6, v0, v0
	s_waitcnt lgkmcnt(0)
	v_fma_f32 v4, v38, v144, -v4
	v_fmac_f32_e32 v6, v4, v4
	v_fmac_f32_e32 v6, v16, v16
	s_waitcnt lgkmcnt(0)
	s_nop 1
	v_add_f32_dpp v6, v6, v6 quad_perm:[1,0,3,2] row_mask:0xf bank_mask:0xf
	s_waitcnt lgkmcnt(0)
	s_nop 1
	v_add_f32_dpp v6, v6, v6 quad_perm:[2,3,0,1] row_mask:0xf bank_mask:0xf
	s_waitcnt lgkmcnt(0)
	s_nop 1
	v_add_f32_dpp v6, v6, v6 row_half_mirror row_mask:0xf bank_mask:0xf
	s_waitcnt lgkmcnt(0)
	s_nop 1
	v_add_f32_dpp v6, v6, v6 row_mirror row_mask:0xf bank_mask:0xf
	ds_bpermute_b32 v18, v208, v6
	s_waitcnt lgkmcnt(0)
	v_add_f32_e32 v6, v6, v18
	v_fmamk_f32 v6, v6, 0x3c000000, v194
	v_rsq_f32_e32 v6, v6
	s_nop 0
	v_mul_f32_e32 v0, v0, v6
	v_mul_f32_e32 v0, v64, v0
	v_cvt_pk_bf16_f32 v0, v0, s0
	ds_write_b16 v68, v0 offset:2560
	v_mul_f32_e32 v0, v2, v6
	v_mul_f32_e32 v0, v65, v0
	v_cvt_pk_bf16_f32 v0, v0, s0
	ds_write_b16 v68, v0 offset:2624
	v_mul_f32_e32 v0, v4, v6
	v_mul_f32_e32 v0, v66, v0
	v_cvt_pk_bf16_f32 v0, v0, s0
	ds_write_b16 v68, v0 offset:2688
	v_mul_f32_e32 v0, v16, v6
	v_mul_f32_e32 v0, v67, v0
	v_cvt_pk_bf16_f32 v0, v0, s0
	ds_write_b16 v68, v0 offset:2752
	v_fma_f32 v0, v7, v143, -v1
	v_fma_f32 v1, v55, v143, -v3
	v_mul_f32_e32 v2, v1, v1
	v_fmac_f32_e32 v2, v0, v0
	v_fma_f32 v3, v39, v143, -v5
	v_fmac_f32_e32 v2, v3, v3
	v_fma_f32 v4, v23, v143, -v17
	v_fmac_f32_e32 v2, v4, v4
	ds_read2st64_b32 v[6:7], v136 offset0:56 offset1:57
	s_waitcnt lgkmcnt(0)
	s_nop 1
	v_add_f32_dpp v2, v2, v2 quad_perm:[1,0,3,2] row_mask:0xf bank_mask:0xf
	s_waitcnt lgkmcnt(0)
	v_fma_f32 v6, v24, v142, -v6
	s_waitcnt lgkmcnt(0)
; __device__ __forceinline__ int crow(int r, int hi) { return (r & 3) + 8 * (r >> 2) + 4 * hi; }
; __device__ __forceinline__ void attn_unit(const bf16* __restrict__ proj, bf16* __restrict__ cat, int b, int h, int qb, float lam, float oscale, const float* __restrict__ subln, const float* __restrict__ cw, char* lds) {
;     ...
;     for (int r = 0; r < 16; ++r) { float s = 0.f;
; #pragma unroll
;       for (int d0 = 0; d0 < 4; ++d0) { const float v = o[d0][r] * rli[r] - X[(d0 * 16 + r) * 64 + lane]; o[d0][r] = v; s += v * v; }
;       s += __shfl_xor(s, 1); s += __shfl_xor(s, 2); s += __shfl_xor(s, 4); s += __shfl_xor(s, 8); s += __shfl_xor(s, 16);
;       const float rs = __builtin_amdgcn_rsqf(s * (1.f / 128.f) + 1e-6f); const int orow = crow(r, hi);
; #pragma unroll
;       for (int d0 = 0; d0 < 4; ++d0) stg[orow * 128 + d0 * 32 + r32] = __float2bfloat16(o[d0][r] * rs * g[d0]); }
	s_nop 1
	v_add_f32_dpp v2, v2, v2 quad_perm:[2,3,0,1] row_mask:0xf bank_mask:0xf
	s_waitcnt lgkmcnt(0)
	s_nop 1
	v_add_f32_dpp v2, v2, v2 row_half_mirror row_mask:0xf bank_mask:0xf
	s_waitcnt lgkmcnt(0)
	s_nop 1
	v_add_f32_dpp v2, v2, v2 row_mirror row_mask:0xf bank_mask:0xf
	ds_bpermute_b32 v5, v208, v2
	s_waitcnt lgkmcnt(0)
	v_add_f32_e32 v2, v2, v5
	v_fmamk_f32 v2, v2, 0x3c000000, v194
	v_rsq_f32_e32 v2, v2
	s_nop 0
	v_mul_f32_e32 v0, v0, v2
	v_mul_f32_e32 v0, v64, v0
	v_cvt_pk_bf16_f32 v0, v0, s0
	ds_write_b16 v68, v0 offset:2816
	v_mul_f32_e32 v0, v1, v2
	v_mul_f32_e32 v0, v65, v0
	v_cvt_pk_bf16_f32 v0, v0, s0
	ds_write_b16 v68, v0 offset:2880
	v_mul_f32_e32 v0, v3, v2
	v_mul_f32_e32 v0, v66, v0
	v_cvt_pk_bf16_f32 v0, v0, s0
	ds_write_b16 v68, v0 offset:2944
	v_mul_f32_e32 v0, v4, v2
	v_mul_f32_e32 v0, v67, v0
	v_cvt_pk_bf16_f32 v0, v0, s0
	ds_write_b16 v68, v0 offset:3008
	ds_read2st64_b32 v[0:1], v136 offset0:8 offset1:9
	ds_read2st64_b32 v[2:3], v136 offset0:24 offset1:25
	ds_read2st64_b32 v[4:5], v136 offset0:40 offset1:41
	s_waitcnt lgkmcnt(0)
	v_fma_f32 v0, v8, v142, -v0
	s_waitcnt lgkmcnt(0)
	v_fma_f32 v2, v56, v142, -v2
	v_mul_f32_e32 v8, v2, v2
	v_fmac_f32_e32 v8, v0, v0
	s_waitcnt lgkmcnt(0)
	v_fma_f32 v4, v40, v142, -v4
	v_fmac_f32_e32 v8, v4, v4
	v_fmac_f32_e32 v8, v6, v6
	s_waitcnt lgkmcnt(0)
	s_nop 1
	v_add_f32_dpp v8, v8, v8 quad_perm:[1,0,3,2] row_mask:0xf bank_mask:0xf
	s_waitcnt lgkmcnt(0)
	s_nop 1
	v_add_f32_dpp v8, v8, v8 quad_perm:[2,3,0,1] row_mask:0xf bank_mask:0xf
	s_waitcnt lgkmcnt(0)
	s_nop 1
	v_add_f32_dpp v8, v8, v8 row_half_mirror row_mask:0xf bank_mask:0xf
	s_waitcnt lgkmcnt(0)
	s_nop 1
	v_add_f32_dpp v8, v8, v8 row_mirror row_mask:0xf bank_mask:0xf
	ds_bpermute_b32 v16, v208, v8
	s_waitcnt lgkmcnt(0)
	v_add_f32_e32 v8, v8, v16
	v_fmamk_f32 v8, v8, 0x3c000000, v194
	v_rsq_f32_e32 v8, v8
	s_nop 0
	v_mul_f32_e32 v0, v0, v8
	v_mul_f32_e32 v0, v64, v0
	v_cvt_pk_bf16_f32 v0, v0, s0
	ds_write_b16 v68, v0 offset:4096
	v_mul_f32_e32 v0, v2, v8
	v_mul_f32_e32 v0, v65, v0
	v_cvt_pk_bf16_f32 v0, v0, s0
	ds_write_b16 v68, v0 offset:4160
	v_mul_f32_e32 v0, v4, v8
	v_mul_f32_e32 v0, v66, v0
	v_cvt_pk_bf16_f32 v0, v0, s0
	ds_write_b16 v68, v0 offset:4224
	v_mul_f32_e32 v0, v6, v8
	v_mul_f32_e32 v0, v67, v0
	v_cvt_pk_bf16_f32 v0, v0, s0
	ds_write_b16 v68, v0 offset:4288
	v_fma_f32 v0, v9, v141, -v1
	v_fma_f32 v1, v57, v141, -v3
	v_mul_f32_e32 v2, v1, v1
	v_fmac_f32_e32 v2, v0, v0
	v_fma_f32 v3, v41, v141, -v5
	v_fmac_f32_e32 v2, v3, v3
	v_fma_f32 v4, v25, v141, -v7
	v_fmac_f32_e32 v2, v4, v4
	ds_read2st64_b32 v[6:7], v136 offset0:58 offset1:59
	s_waitcnt lgkmcnt(0)
	s_nop 1
	v_add_f32_dpp v2, v2, v2 quad_perm:[1,0,3,2] row_mask:0xf bank_mask:0xf
	s_waitcnt lgkmcnt(0)
	v_fma_f32 v6, v26, v140, -v6
	s_waitcnt lgkmcnt(0)
	s_nop 1
	v_add_f32_dpp v2, v2, v2 quad_perm:[2,3,0,1] row_mask:0xf bank_mask:0xf
	s_waitcnt lgkmcnt(0)
	s_nop 1
	v_add_f32_dpp v2, v2, v2 row_half_mirror row_mask:0xf bank_mask:0xf
	s_waitcnt lgkmcnt(0)
	s_nop 1
	v_add_f32_dpp v2, v2, v2 row_mirror row_mask:0xf bank_mask:0xf
	ds_bpermute_b32 v5, v208, v2
	s_waitcnt lgkmcnt(0)
	v_add_f32_e32 v2, v2, v5
	v_fmamk_f32 v2, v2, 0x3c000000, v194
	v_rsq_f32_e32 v2, v2
	s_nop 0
	v_mul_f32_e32 v0, v0, v2
	v_mul_f32_e32 v0, v64, v0
	v_cvt_pk_bf16_f32 v0, v0, s0
	ds_write_b16 v68, v0 offset:4352
	v_mul_f32_e32 v0, v1, v2
	v_mul_f32_e32 v0, v65, v0
	v_cvt_pk_bf16_f32 v0, v0, s0
	ds_write_b16 v68, v0 offset:4416
	v_mul_f32_e32 v0, v3, v2
	v_mul_f32_e32 v0, v66, v0
	v_cvt_pk_bf16_f32 v0, v0, s0
	ds_write_b16 v68, v0 offset:4480
	v_mul_f32_e32 v0, v4, v2
	v_mul_f32_e32 v0, v67, v0
	v_cvt_pk_bf16_f32 v0, v0, s0
	ds_write_b16 v68, v0 offset:4544
	ds_read2st64_b32 v[0:1], v136 offset0:10 offset1:11
	ds_read2st64_b32 v[2:3], v136 offset0:26 offset1:27
	ds_read2st64_b32 v[4:5], v136 offset0:42 offset1:43
	s_waitcnt lgkmcnt(0)
	v_fma_f32 v0, v10, v140, -v0
	s_waitcnt lgkmcnt(0)
	v_fma_f32 v2, v58, v140, -v2
	v_mul_f32_e32 v8, v2, v2
	v_fmac_f32_e32 v8, v0, v0
	s_waitcnt lgkmcnt(0)
	v_fma_f32 v4, v42, v140, -v4
	v_fmac_f32_e32 v8, v4, v4
	v_fmac_f32_e32 v8, v6, v6
	s_waitcnt lgkmcnt(0)
	s_nop 1
	v_add_f32_dpp v8, v8, v8 quad_perm:[1,0,3,2] row_mask:0xf bank_mask:0xf
	s_waitcnt lgkmcnt(0)
	s_nop 1
	v_add_f32_dpp v8, v8, v8 quad_perm:[2,3,0,1] row_mask:0xf bank_mask:0xf
	s_waitcnt lgkmcnt(0)
	s_nop 1
	v_add_f32_dpp v8, v8, v8 row_half_mirror row_mask:0xf bank_mask:0xf
	s_waitcnt lgkmcnt(0)
	s_nop 1
	v_add_f32_dpp v8, v8, v8 row_mirror row_mask:0xf bank_mask:0xf
	ds_bpermute_b32 v9, v208, v8
	s_waitcnt lgkmcnt(0)
	v_add_f32_e32 v8, v8, v9
	v_fmamk_f32 v8, v8, 0x3c000000, v194
	v_rsq_f32_e32 v8, v8
	s_nop 0
	v_mul_f32_e32 v0, v0, v8
	v_mul_f32_e32 v0, v64, v0
	v_cvt_pk_bf16_f32 v0, v0, s0
	ds_write_b16 v68, v0 offset:4608
	v_mul_f32_e32 v0, v2, v8
	v_mul_f32_e32 v0, v65, v0
	v_cvt_pk_bf16_f32 v0, v0, s0
	ds_write_b16 v68, v0 offset:4672
	v_mul_f32_e32 v0, v4, v8
	v_mul_f32_e32 v0, v66, v0
	v_cvt_pk_bf16_f32 v0, v0, s0
	ds_write_b16 v68, v0 offset:4736
	v_mul_f32_e32 v0, v6, v8
	v_mul_f32_e32 v0, v67, v0
	v_cvt_pk_bf16_f32 v0, v0, s0
	ds_write_b16 v68, v0 offset:4800
	v_fma_f32 v0, v11, v139, -v1
	v_fma_f32 v1, v59, v139, -v3
	v_mul_f32_e32 v2, v1, v1
	v_fmac_f32_e32 v2, v0, v0
	v_fma_f32 v3, v43, v139, -v5
	v_fmac_f32_e32 v2, v3, v3
	v_fma_f32 v4, v27, v139, -v7
	v_fmac_f32_e32 v2, v4, v4
	ds_read2st64_b32 v[6:7], v136 offset0:60 offset1:61
	s_waitcnt lgkmcnt(0)
	s_nop 1
	v_add_f32_dpp v2, v2, v2 quad_perm:[1,0,3,2] row_mask:0xf bank_mask:0xf
	s_waitcnt lgkmcnt(0)
	v_fma_f32 v6, v28, v138, -v6
	s_waitcnt lgkmcnt(0)
	s_nop 1
	v_add_f32_dpp v2, v2, v2 quad_perm:[2,3,0,1] row_mask:0xf bank_mask:0xf
	s_waitcnt lgkmcnt(0)
; __device__ __forceinline__ int crow(int r, int hi) { return (r & 3) + 8 * (r >> 2) + 4 * hi; }
; __device__ __forceinline__ void attn_unit(const bf16* __restrict__ proj, bf16* __restrict__ cat, int b, int h, int qb, float lam, float oscale, const float* __restrict__ subln, const float* __restrict__ cw, char* lds) {
;     ...
;     for (int r = 0; r < 16; ++r) { float s = 0.f;
; #pragma unroll
;       for (int d0 = 0; d0 < 4; ++d0) { const float v = o[d0][r] * rli[r] - X[(d0 * 16 + r) * 64 + lane]; o[d0][r] = v; s += v * v; }
;       s += __shfl_xor(s, 1); s += __shfl_xor(s, 2); s += __shfl_xor(s, 4); s += __shfl_xor(s, 8); s += __shfl_xor(s, 16);
;       const float rs = __builtin_amdgcn_rsqf(s * (1.f / 128.f) + 1e-6f); const int orow = crow(r, hi);
; #pragma unroll
;       for (int d0 = 0; d0 < 4; ++d0) stg[orow * 128 + d0 * 32 + r32] = __float2bfloat16(o[d0][r] * rs * g[d0]); }
	s_nop 1
	v_add_f32_dpp v2, v2, v2 row_half_mirror row_mask:0xf bank_mask:0xf
	s_waitcnt lgkmcnt(0)
	s_nop 1
	v_add_f32_dpp v2, v2, v2 row_mirror row_mask:0xf bank_mask:0xf
	ds_bpermute_b32 v5, v208, v2
	s_waitcnt lgkmcnt(0)
	v_add_f32_e32 v2, v2, v5
	v_fmamk_f32 v2, v2, 0x3c000000, v194
	v_rsq_f32_e32 v2, v2
	s_nop 0
	v_mul_f32_e32 v0, v0, v2
	v_mul_f32_e32 v0, v64, v0
	v_cvt_pk_bf16_f32 v0, v0, s0
	ds_write_b16 v68, v0 offset:4864
	v_mul_f32_e32 v0, v1, v2
	v_mul_f32_e32 v0, v65, v0
	v_cvt_pk_bf16_f32 v0, v0, s0
	ds_write_b16 v68, v0 offset:4928
	v_mul_f32_e32 v0, v3, v2
	v_mul_f32_e32 v0, v66, v0
	v_cvt_pk_bf16_f32 v0, v0, s0
	ds_write_b16 v68, v0 offset:4992
	v_mul_f32_e32 v0, v4, v2
	v_mul_f32_e32 v0, v67, v0
	v_cvt_pk_bf16_f32 v0, v0, s0
	ds_write_b16 v68, v0 offset:5056
	ds_read2st64_b32 v[0:1], v136 offset0:12 offset1:13
	ds_read2st64_b32 v[2:3], v136 offset0:28 offset1:29
	ds_read2st64_b32 v[4:5], v136 offset0:44 offset1:45
	s_waitcnt lgkmcnt(0)
	v_fma_f32 v0, v12, v138, -v0
	s_waitcnt lgkmcnt(0)
	v_fma_f32 v2, v60, v138, -v2
	v_mul_f32_e32 v8, v2, v2
	v_fmac_f32_e32 v8, v0, v0
	s_waitcnt lgkmcnt(0)
	v_fma_f32 v4, v44, v138, -v4
	v_fmac_f32_e32 v8, v4, v4
	v_fmac_f32_e32 v8, v6, v6
	s_waitcnt lgkmcnt(0)
	s_nop 1
	v_add_f32_dpp v8, v8, v8 quad_perm:[1,0,3,2] row_mask:0xf bank_mask:0xf
	s_waitcnt lgkmcnt(0)
	s_nop 1
	v_add_f32_dpp v8, v8, v8 quad_perm:[2,3,0,1] row_mask:0xf bank_mask:0xf
	s_waitcnt lgkmcnt(0)
	s_nop 1
	v_add_f32_dpp v8, v8, v8 row_half_mirror row_mask:0xf bank_mask:0xf
	s_waitcnt lgkmcnt(0)
	s_nop 1
	v_add_f32_dpp v8, v8, v8 row_mirror row_mask:0xf bank_mask:0xf
	ds_bpermute_b32 v9, v208, v8
	s_waitcnt lgkmcnt(0)
	v_add_f32_e32 v8, v8, v9
	v_fmamk_f32 v8, v8, 0x3c000000, v194
	v_rsq_f32_e32 v8, v8
	s_nop 0
	v_mul_f32_e32 v0, v0, v8
	v_mul_f32_e32 v0, v64, v0
	v_cvt_pk_bf16_f32 v0, v0, s0
	ds_write_b16 v68, v0 offset:6144
	v_mul_f32_e32 v0, v2, v8
	v_mul_f32_e32 v0, v65, v0
	v_cvt_pk_bf16_f32 v0, v0, s0
	ds_write_b16 v68, v0 offset:6208
	v_mul_f32_e32 v0, v4, v8
	v_mul_f32_e32 v0, v66, v0
	v_cvt_pk_bf16_f32 v0, v0, s0
	ds_write_b16 v68, v0 offset:6272
	v_mul_f32_e32 v0, v6, v8
	v_mul_f32_e32 v0, v67, v0
	v_cvt_pk_bf16_f32 v0, v0, s0
	ds_write_b16 v68, v0 offset:6336
	v_fma_f32 v0, v13, v137, -v1
	v_fma_f32 v1, v61, v137, -v3
	v_mul_f32_e32 v2, v1, v1
	v_fmac_f32_e32 v2, v0, v0
	v_fma_f32 v3, v45, v137, -v5
	v_fmac_f32_e32 v2, v3, v3
	v_fma_f32 v4, v29, v137, -v7
	v_fmac_f32_e32 v2, v4, v4
	ds_read2st64_b32 v[6:7], v136 offset0:62 offset1:63
	s_waitcnt lgkmcnt(0)
	s_nop 1
	v_add_f32_dpp v2, v2, v2 quad_perm:[1,0,3,2] row_mask:0xf bank_mask:0xf
	s_waitcnt lgkmcnt(0)
	v_fma_f32 v6, v30, v135, -v6
	s_waitcnt lgkmcnt(0)
	s_nop 1
	v_add_f32_dpp v2, v2, v2 quad_perm:[2,3,0,1] row_mask:0xf bank_mask:0xf
	s_waitcnt lgkmcnt(0)
	s_nop 1
	v_add_f32_dpp v2, v2, v2 row_half_mirror row_mask:0xf bank_mask:0xf
	s_waitcnt lgkmcnt(0)
	s_nop 1
	v_add_f32_dpp v2, v2, v2 row_mirror row_mask:0xf bank_mask:0xf
	ds_bpermute_b32 v5, v208, v2
	s_waitcnt lgkmcnt(0)
	v_add_f32_e32 v2, v2, v5
	v_fmamk_f32 v2, v2, 0x3c000000, v194
	v_rsq_f32_e32 v2, v2
	s_nop 0
	v_mul_f32_e32 v0, v0, v2
	v_mul_f32_e32 v0, v64, v0
	v_cvt_pk_bf16_f32 v0, v0, s0
	ds_write_b16 v68, v0 offset:6400
	v_mul_f32_e32 v0, v1, v2
	v_mul_f32_e32 v0, v65, v0
	v_cvt_pk_bf16_f32 v0, v0, s0
	ds_write_b16 v68, v0 offset:6464
	v_mul_f32_e32 v0, v3, v2
	v_mul_f32_e32 v0, v66, v0
	v_cvt_pk_bf16_f32 v0, v0, s0
	ds_write_b16 v68, v0 offset:6528
	v_mul_f32_e32 v0, v4, v2
	v_mul_f32_e32 v0, v67, v0
	v_cvt_pk_bf16_f32 v0, v0, s0
	ds_write_b16 v68, v0 offset:6592
	ds_read2st64_b32 v[0:1], v136 offset0:14 offset1:15
	ds_read2st64_b32 v[2:3], v136 offset0:30 offset1:31
	ds_read2st64_b32 v[4:5], v136 offset0:46 offset1:47
	s_waitcnt lgkmcnt(0)
	v_fma_f32 v0, v14, v135, -v0
	s_waitcnt lgkmcnt(0)
	v_fma_f32 v2, v62, v135, -v2
	v_mul_f32_e32 v8, v2, v2
	v_fmac_f32_e32 v8, v0, v0
	s_waitcnt lgkmcnt(0)
	v_fma_f32 v4, v46, v135, -v4
	v_fmac_f32_e32 v8, v4, v4
	v_fmac_f32_e32 v8, v6, v6
	s_waitcnt lgkmcnt(0)
	s_nop 1
	v_add_f32_dpp v8, v8, v8 quad_perm:[1,0,3,2] row_mask:0xf bank_mask:0xf
	s_waitcnt lgkmcnt(0)
; __device__ __forceinline__ int crow(int r, int hi) { return (r & 3) + 8 * (r >> 2) + 4 * hi; }
; __device__ __forceinline__ void attn_unit(const bf16* __restrict__ proj, bf16* __restrict__ cat, int b, int h, int qb, float lam, float oscale, const float* __restrict__ subln, const float* __restrict__ cw, char* lds) {
;     ...
;     for (int r = 0; r < 16; ++r) { float s = 0.f;
; #pragma unroll
;       for (int d0 = 0; d0 < 4; ++d0) { const float v = o[d0][r] * rli[r] - X[(d0 * 16 + r) * 64 + lane]; o[d0][r] = v; s += v * v; }
;       s += __shfl_xor(s, 1); s += __shfl_xor(s, 2); s += __shfl_xor(s, 4); s += __shfl_xor(s, 8); s += __shfl_xor(s, 16);
;       const float rs = __builtin_amdgcn_rsqf(s * (1.f / 128.f) + 1e-6f); const int orow = crow(r, hi);
; #pragma unroll
;       for (int d0 = 0; d0 < 4; ++d0) stg[orow * 128 + d0 * 32 + r32] = __float2bfloat16(o[d0][r] * rs * g[d0]); }
;     asm volatile("s_waitcnt lgkmcnt(0)" ::: "memory");
;     bf16* Ow = cat + (rowbase + qb * QROWS + rg * 32) * LDC + h * 128;
; #pragma unroll
;     for (int i = 0; i < 8; ++i) { const int row = i * 4 + (lane >> 4), ch = lane & 15; const u32x4 v = *(const u32x4*)(stg + row * 128 + ch * 8); *(u32x4*)(Ow + (long)row * LDC + ch * 8) = v; }
	s_nop 1
	v_add_f32_dpp v8, v8, v8 quad_perm:[2,3,0,1] row_mask:0xf bank_mask:0xf
	s_waitcnt lgkmcnt(0)
	s_nop 1
	v_add_f32_dpp v8, v8, v8 row_half_mirror row_mask:0xf bank_mask:0xf
	s_waitcnt lgkmcnt(0)
	s_nop 1
	v_add_f32_dpp v8, v8, v8 row_mirror row_mask:0xf bank_mask:0xf
	ds_bpermute_b32 v9, v208, v8
	s_waitcnt lgkmcnt(0)
	v_add_f32_e32 v8, v8, v9
	v_fmamk_f32 v8, v8, 0x3c000000, v194
	v_rsq_f32_e32 v8, v8
	s_nop 0
	v_mul_f32_e32 v0, v0, v8
	v_mul_f32_e32 v0, v64, v0
	v_cvt_pk_bf16_f32 v0, v0, s0
	ds_write_b16 v68, v0 offset:6656
	v_mul_f32_e32 v0, v2, v8
	v_mul_f32_e32 v0, v65, v0
	v_cvt_pk_bf16_f32 v0, v0, s0
	ds_write_b16 v68, v0 offset:6720
	v_mul_f32_e32 v0, v4, v8
	v_mul_f32_e32 v0, v66, v0
	v_cvt_pk_bf16_f32 v0, v0, s0
	ds_write_b16 v68, v0 offset:6784
	v_mul_f32_e32 v0, v6, v8
	v_mul_f32_e32 v0, v67, v0
	v_cvt_pk_bf16_f32 v0, v0, s0
	ds_write_b16 v68, v0 offset:6848
	v_fma_f32 v0, v15, v134, -v1
	v_fma_f32 v1, v63, v134, -v3
	v_mul_f32_e32 v2, v1, v1
	v_fmac_f32_e32 v2, v0, v0
	v_fma_f32 v3, v47, v134, -v5
	v_fmac_f32_e32 v2, v3, v3
	v_fma_f32 v4, v31, v134, -v7
	v_fmac_f32_e32 v2, v4, v4
	v_lshrrev_b32_e32 v8, 4, v177
	s_waitcnt lgkmcnt(0)
	s_nop 1
	v_add_f32_dpp v2, v2, v2 quad_perm:[1,0,3,2] row_mask:0xf bank_mask:0xf
	s_waitcnt lgkmcnt(0)
	s_nop 1
	v_add_f32_dpp v2, v2, v2 quad_perm:[2,3,0,1] row_mask:0xf bank_mask:0xf
	s_waitcnt lgkmcnt(0)
	s_nop 1
	v_add_f32_dpp v2, v2, v2 row_half_mirror row_mask:0xf bank_mask:0xf
	s_waitcnt lgkmcnt(0)
	s_nop 1
	v_add_f32_dpp v2, v2, v2 row_mirror row_mask:0xf bank_mask:0xf
	ds_bpermute_b32 v5, v208, v2
	s_waitcnt lgkmcnt(0)
	v_add_f32_e32 v2, v2, v5
	v_fmamk_f32 v2, v2, 0x3c000000, v194
	v_rsq_f32_e32 v2, v2
	s_nop 0
	v_mul_f32_e32 v0, v0, v2
	v_mul_f32_e32 v0, v64, v0
	v_cvt_pk_bf16_f32 v0, v0, s0
	ds_write_b16 v68, v0 offset:6912
	v_mul_f32_e32 v0, v1, v2
	v_mul_f32_e32 v0, v65, v0
	v_cvt_pk_bf16_f32 v0, v0, s0
	ds_write_b16 v68, v0 offset:6976
	v_mul_f32_e32 v0, v3, v2
	v_mul_f32_e32 v0, v66, v0
	v_cvt_pk_bf16_f32 v0, v0, s0
	ds_write_b16 v68, v0 offset:7040
	v_mul_f32_e32 v0, v4, v2
	v_mul_f32_e32 v0, v67, v0
	v_cvt_pk_bf16_f32 v0, v0, s0
	ds_write_b16 v68, v0 offset:7104
	v_lshlrev_b32_e32 v0, 1, v178
	v_and_b32_e32 v162, 0xf0, v0
	v_add_u32_e32 v9, s20, v162
	s_waitcnt lgkmcnt(0)
	v_lshl_add_u32 v0, v8, 8, v9
	ds_read_b128 v[0:3], v0
	v_lshl_add_u64 v[4:5], s[24:25], 0, v[162:163]
	v_lshlrev_b32_e32 v162, 12, v8
	v_lshl_add_u64 v[6:7], v[4:5], 0, v[162:163]
	s_waitcnt lgkmcnt(0)
	global_store_dwordx4 v[6:7], v[0:3], off sc1
	v_or_b32_e32 v6, 4, v8
	s_nop 0
	v_lshl_add_u32 v0, v6, 8, v9
	ds_read_b128 v[0:3], v0
	v_lshlrev_b32_e32 v162, 12, v6
	v_lshl_add_u64 v[6:7], v[4:5], 0, v[162:163]
	s_waitcnt lgkmcnt(0)
	global_store_dwordx4 v[6:7], v[0:3], off sc1
	v_or_b32_e32 v6, 8, v8
	s_nop 0
	v_lshl_add_u32 v0, v6, 8, v9
	ds_read_b128 v[0:3], v0
	v_lshlrev_b32_e32 v162, 12, v6
	v_lshl_add_u64 v[6:7], v[4:5], 0, v[162:163]
	s_waitcnt lgkmcnt(0)
	global_store_dwordx4 v[6:7], v[0:3], off sc1
	v_or_b32_e32 v6, 12, v8
	s_nop 0
	v_lshl_add_u32 v0, v6, 8, v9
	ds_read_b128 v[0:3], v0
	v_lshlrev_b32_e32 v162, 12, v6
	v_lshl_add_u64 v[6:7], v[4:5], 0, v[162:163]
	s_waitcnt lgkmcnt(0)
	global_store_dwordx4 v[6:7], v[0:3], off sc1
	v_or_b32_e32 v6, 16, v8
	s_nop 0
	v_lshl_add_u32 v0, v6, 8, v9
	ds_read_b128 v[0:3], v0
	v_lshlrev_b32_e32 v162, 12, v6
	v_lshl_add_u64 v[6:7], v[4:5], 0, v[162:163]
	s_waitcnt lgkmcnt(0)
	global_store_dwordx4 v[6:7], v[0:3], off sc1
	v_or_b32_e32 v6, 20, v8
	s_nop 0
	v_lshl_add_u32 v0, v6, 8, v9
	ds_read_b128 v[0:3], v0
	v_lshlrev_b32_e32 v162, 12, v6
	v_lshl_add_u64 v[6:7], v[4:5], 0, v[162:163]
	s_waitcnt lgkmcnt(0)
	global_store_dwordx4 v[6:7], v[0:3], off sc1
	v_or_b32_e32 v6, 24, v8
	s_nop 0
	v_lshl_add_u32 v0, v6, 8, v9
	ds_read_b128 v[0:3], v0
	v_lshlrev_b32_e32 v162, 12, v6
	v_lshl_add_u64 v[6:7], v[4:5], 0, v[162:163]
	s_waitcnt lgkmcnt(0)
	global_store_dwordx4 v[6:7], v[0:3], off sc1
	v_or_b32_e32 v6, 28, v8
	s_nop 0
	v_lshl_add_u32 v0, v6, 8, v9
	ds_read_b128 v[0:3], v0
	v_lshlrev_b32_e32 v162, 12, v6
	v_lshl_add_u64 v[4:5], v[4:5], 0, v[162:163]
	s_waitcnt lgkmcnt(0)
	global_store_dwordx4 v[4:5], v[0:3], off sc1
	s_branch .LBB0_207
